# h-init copy loads batched; slab consumers: static piece counts, two buffer sets in flight; s_setprio 2 on WKV scan waves
# speedup vs baseline: 1.0165x; 1.0065x over previous
.LBB0_165:
	s_lshl_b64 s[42:43], s[56:57], 12
	s_add_u32 s6, s6, s42
	s_addc_u32 s7, s7, s43
	global_load_dwordx4 v[56:59], v30, s[6:7]
	global_load_dwordx4 v[10:13], v30, s[6:7] offset:1024
	global_load_dwordx4 v[14:17], v30, s[6:7] offset:2048
	global_load_dwordx4 v[2:5], v30, s[6:7] offset:3072
	v_readlane_b32 s44, v250, 13
	v_readlane_b32 s46, v250, 15
	v_readlane_b32 s47, v250, 16
	s_mov_b32 s1, 0xf800000
	s_add_i32 s0, s0, s52
	v_lshl_add_u64 v[6:7], s[46:47], 0, v[22:23]
	v_add_co_u32_e32 v6, vcc, 0x7506000, v6
	v_lshl_add_u64 v[22:23], v[22:23], 0, s[74:75]
	s_nop 0
	v_addc_co_u32_e32 v7, vcc, 0, v7, vcc
	v_readlane_b32 s45, v250, 14
	v_readlane_b32 s48, v250, 17
	v_readlane_b32 s49, v250, 18
	v_readlane_b32 s50, v250, 19
	v_readlane_b32 s51, v250, 20
	s_waitcnt vmcnt(0)
	global_store_dwordx4 v[6:7], v[56:59], off
	global_store_dwordx4 v[6:7], v[10:13], off offset:1024
	global_store_dwordx4 v[6:7], v[14:17], off offset:2048
	global_store_dwordx4 v[6:7], v[2:5], off offset:3072
	v_mul_f32_e32 v43, v3, v3
	v_mov_b64_e32 v[8:9], v[58:59]
	v_mov_b64_e32 v[6:7], v[56:57]
	v_mul_f32_e32 v31, v2, v2
	v_mul_f32_e32 v46, v4, v4
	v_mul_f32_e32 v47, v5, v5
	v_pk_mul_f32 v[32:33], v[8:9], v[8:9]
	v_pk_mul_f32 v[34:35], v[6:7], v[6:7]
	v_pk_mul_f32 v[36:37], v[12:13], v[12:13]
	v_pk_mul_f32 v[38:39], v[10:11], v[10:11]
	v_pk_mov_b32 v[44:45], v[34:35], v[32:33] op_sel:[1,0]
	v_mov_b32_e32 v35, v33
	v_pk_mov_b32 v[32:33], v[38:39], v[36:37] op_sel:[1,0]
	v_mov_b32_e32 v39, v37
	v_mul_f32_e32 v40, v15, v15
	v_mul_f32_e32 v42, v17, v17
	v_pk_add_f32 v[34:35], v[44:45], v[34:35]
	v_pk_add_f32 v[32:33], v[32:33], v[38:39]
	v_pk_fma_f32 v[36:37], v[14:15], v[14:15], v[40:41] op_sel_hi:[1,1,0]
	v_pk_fma_f32 v[40:41], v[16:17], v[16:17], v[42:43] op_sel_hi:[1,1,0]
	v_pk_add_f32 v[34:35], v[34:35], v[34:35] op_sel:[0,1] op_sel_hi:[1,0]
	v_pk_add_f32 v[32:33], v[32:33], v[32:33] op_sel:[0,1] op_sel_hi:[1,0]
	v_mov_b32_e32 v37, v46
	v_mov_b32_e32 v41, v47
	v_mov_b32_e32 v35, v31
	v_mov_b32_e32 v33, v43
	v_pk_add_f32 v[36:37], v[36:37], v[40:41]
	v_pk_add_f32 v[32:33], v[34:35], v[32:33]
	s_nop 0
	v_pk_add_f32 v[32:33], v[32:33], v[36:37]
	s_nop 0
	v_add_f32_e32 v31, v32, v33
	ds_bpermute_b32 v40, v24, v31
	global_load_dwordx4 v[32:35], v[18:19], off
	global_load_dwordx4 v[36:39], v[18:19], off offset:1024
	s_waitcnt lgkmcnt(0)
	v_add_f32_e32 v31, v31, v40
	global_load_dwordx4 v[40:43], v[18:19], off offset:2048
	global_load_dwordx4 v[44:47], v[18:19], off offset:3072
	ds_bpermute_b32 v48, v25, v31
	s_waitcnt lgkmcnt(0)
	v_add_f32_e32 v31, v31, v48
	ds_bpermute_b32 v48, v26, v31
	s_waitcnt lgkmcnt(0)
	v_add_f32_e32 v31, v31, v48
	ds_bpermute_b32 v48, v27, v31
	s_waitcnt lgkmcnt(0)
	v_add_f32_e32 v31, v31, v48
	ds_bpermute_b32 v48, v28, v31
	s_waitcnt lgkmcnt(0)
	v_add_f32_e32 v31, v31, v48
	ds_bpermute_b32 v50, v29, v31
	v_lshl_add_u64 v[48:49], s[46:47], 0, v[20:21]
	v_lshl_add_u64 v[20:21], v[20:21], 0, s[78:79]
	s_waitcnt lgkmcnt(0)
	v_add_f32_e32 v31, v31, v50
	v_fmamk_f32 v31, v31, 0x3a800000, v1
	v_mul_f32_e32 v50, 0x4f800000, v31
	v_cmp_gt_f32_e32 vcc, s1, v31
	s_mov_b32 s1, 0xb606000
	v_add_co_u32_e64 v48, s[6:7], s1, v48
	v_cndmask_b32_e32 v31, v31, v50, vcc
	v_sqrt_f32_e32 v50, v31
	v_addc_co_u32_e64 v49, s[6:7], 0, v49, s[6:7]
	s_add_i32 s1, s0, 0x4080
	v_add_u32_e32 v51, -1, v50
	v_add_u32_e32 v52, 1, v50
	v_fma_f32 v53, -v51, v50, v31
	v_fma_f32 v54, -v52, v50, v31
	v_cmp_ge_f32_e64 s[6:7], 0, v53
	s_cmpk_gt_i32 s1, 0x40ff
	s_nop 0
	v_cndmask_b32_e64 v50, v50, v51, s[6:7]
	v_cmp_lt_f32_e64 s[6:7], 0, v54
	s_nop 1
	v_cndmask_b32_e64 v50, v50, v52, s[6:7]
	v_mul_f32_e32 v51, 0x37800000, v50
	v_cndmask_b32_e32 v50, v50, v51, vcc
	v_cmp_class_f32_e32 vcc, v31, v87
	s_nop 1
	v_cndmask_b32_e32 v31, v50, v31, vcc
	v_div_scale_f32 v50, s[6:7], v31, v31, 1.0
	v_rcp_f32_e32 v51, v50
	v_div_scale_f32 v52, vcc, 1.0, v31, 1.0
	v_fma_f32 v53, -v50, v51, 1.0
	v_fmac_f32_e32 v51, v53, v51
	v_mul_f32_e32 v53, v52, v51
	v_fma_f32 v54, -v50, v53, v52
	v_fmac_f32_e32 v53, v54, v51
	v_fma_f32 v50, -v50, v53, v52
	v_div_fmas_f32 v50, v50, v51, v53
	v_div_fixup_f32 v50, v50, v31, 1.0
	v_pk_mul_f32 v[6:7], v[6:7], v[50:51] op_sel_hi:[1,0]
	v_pk_mul_f32 v[8:9], v[8:9], v[50:51] op_sel_hi:[1,0]
	v_pk_mul_f32 v[10:11], v[10:11], v[50:51] op_sel_hi:[1,0]
	v_pk_mul_f32 v[12:13], v[12:13], v[50:51] op_sel_hi:[1,0]
	v_pk_mul_f32 v[14:15], v[14:15], v[50:51] op_sel_hi:[1,0]
	v_pk_mul_f32 v[16:17], v[16:17], v[50:51] op_sel_hi:[1,0]
	v_pk_mul_f32 v[2:3], v[2:3], v[50:51] op_sel_hi:[1,0]
	v_pk_mul_f32 v[4:5], v[4:5], v[50:51] op_sel_hi:[1,0]
	s_waitcnt vmcnt(3)
	v_pk_mul_f32 v[8:9], v[34:35], v[8:9]
	v_pk_mul_f32 v[6:7], v[32:33], v[6:7]
	s_waitcnt vmcnt(2)
	v_pk_mul_f32 v[12:13], v[38:39], v[12:13]
	v_pk_mul_f32 v[10:11], v[36:37], v[10:11]
	s_waitcnt vmcnt(1)
	v_pk_mul_f32 v[16:17], v[42:43], v[16:17]
	v_pk_mul_f32 v[14:15], v[40:41], v[14:15]
	s_waitcnt vmcnt(0)
	v_pk_mul_f32 v[4:5], v[46:47], v[4:5]
	v_pk_mul_f32 v[2:3], v[44:45], v[2:3]
	v_bfe_u32 v31, v6, 16, 1
	v_bfe_u32 v33, v8, 16, 1
	v_bfe_u32 v32, v7, 16, 1
	v_bfe_u32 v34, v9, 16, 1
	v_bfe_u32 v35, v10, 16, 1
	v_bfe_u32 v37, v12, 16, 1
	v_bfe_u32 v39, v14, 16, 1
	v_bfe_u32 v41, v16, 16, 1
	v_bfe_u32 v43, v2, 16, 1
	v_bfe_u32 v44, v3, 16, 1
	v_bfe_u32 v45, v4, 16, 1
	v_bfe_u32 v46, v5, 16, 1
	v_add3_u32 v6, v6, v31, s33
	v_add3_u32 v8, v8, v33, s33
	v_bfe_u32 v36, v11, 16, 1
	v_bfe_u32 v38, v13, 16, 1
	v_bfe_u32 v40, v15, 16, 1
	v_bfe_u32 v42, v17, 16, 1
	v_add3_u32 v7, v7, v32, s33
	v_add3_u32 v9, v9, v34, s33
	v_add3_u32 v10, v10, v35, s33
	v_add3_u32 v12, v12, v37, s33
	v_add3_u32 v14, v14, v39, s33
	v_add3_u32 v16, v16, v41, s33
	v_add3_u32 v2, v2, v43, s33
	v_add3_u32 v31, v3, v44, s33
	v_add3_u32 v3, v4, v45, s33
	v_add3_u32 v32, v5, v46, s33
	v_lshrrev_b32_e32 v4, 16, v6
	v_lshrrev_b32_e32 v5, 16, v8
	v_add3_u32 v11, v11, v36, s33
	v_add3_u32 v13, v13, v38, s33
	v_add3_u32 v15, v15, v40, s33
	v_add3_u32 v17, v17, v42, s33
	v_lshrrev_b32_e32 v6, 16, v10
	v_lshrrev_b32_e32 v8, 16, v12
	v_lshrrev_b32_e32 v10, 16, v14
	v_lshrrev_b32_e32 v12, 16, v16
	v_lshrrev_b32_e32 v14, 16, v2
	v_lshrrev_b32_e32 v16, 16, v3
	v_and_or_b32 v2, v7, s89, v4
	v_and_or_b32 v3, v9, s89, v5
	v_and_or_b32 v4, v11, s89, v6
	v_and_or_b32 v5, v13, s89, v8
	v_and_or_b32 v6, v15, s89, v10
	v_and_or_b32 v7, v17, s89, v12
	v_and_or_b32 v8, v31, s89, v14
	v_and_or_b32 v9, v32, s89, v16
	global_store_dwordx2 v[48:49], v[2:3], off
	global_store_dwordx2 v[48:49], v[4:5], off offset:512
	global_store_dwordx2 v[48:49], v[6:7], off offset:1024
	global_store_dwordx2 v[48:49], v[8:9], off offset:1536
	s_cbranch_scc1 .LBB0_8

.LBB0_3018:
	v_readlane_b32 s12, v252, 30
	v_readlane_b32 s13, v252, 31
	v_mov_b32_e32 v0, v226
	s_andn2_b64 vcc, exec, s[12:13]
	s_mov_b32 s26, 0xb606000
	s_cbranch_vccnz .LBB0_3017
	v_readlane_b32 s14, v250, 6
	s_cmp_gt_u32 s14, 0xff
	s_cbranch_scc1 .Lslab_skip_a
	v_and_b32_e32 v2, 63, v226
	v_lshlrev_b32_e32 v2, 4, v2
	v_lshl_add_u32 v60, s14, 13, v2
	v_mov_b32_e32 v61, 0
	v_lshl_add_u32 v2, s14, 12, v2
	v_mov_b32_e32 v3, 0
	v_readlane_b32 s18, v254, 55
	s_cmp_eq_u32 s18, 1
	s_cbranch_scc1 .Lslab_a_l1
	v_readlane_b32 s14, v250, 15
	v_readlane_b32 s18, v250, 16
	s_add_u32 s12, s14, 0xb506000
	s_addc_u32 s13, s18, 0
	v_lshl_add_u64 v[4:5], s[12:13], 0, v[2:3]
	global_load_dwordx4 v[8:11], v[4:5], off sc1
	global_load_dwordx4 v[12:15], v[4:5], off offset:1024 sc1
	global_load_dwordx4 v[16:19], v[4:5], off offset:2048 sc1
	global_load_dwordx4 v[20:23], v[4:5], off offset:3072 sc1
	v_readlane_b32 s14, v250, 15
	v_readlane_b32 s18, v250, 16
	s_add_u32 s12, s14, 0x274e6000
	s_addc_u32 s13, s18, 0
	v_lshl_add_u64 v[24:25], s[12:13], 0, v[2:3]
	s_mov_b64 s[12:13], 0x100000
	v_lshl_add_u64 v[26:27], v[24:25], 0, s[12:13]
	v_lshl_add_u64 v[78:79], v[26:27], 0, s[12:13]
	v_lshl_add_u64 v[98:99], v[78:79], 0, s[12:13]
	s_mov_b64 s[12:13], 0x400000
	v_readlane_b32 s14, v254, 55
	s_add_i32 s14, s14, 1
	s_bfe_u32 s14, s14, 0x10001
	s_sub_i32 s18, 2, s14
	global_load_dwordx4 v[28:31], v[24:25], off
	global_load_dwordx4 v[32:35], v[24:25], off offset:1024
	global_load_dwordx4 v[36:39], v[24:25], off offset:2048
	global_load_dwordx4 v[40:43], v[24:25], off offset:3072
	global_load_dwordx4 v[44:47], v[26:27], off
	global_load_dwordx4 v[48:51], v[26:27], off offset:1024
	global_load_dwordx4 v[52:55], v[26:27], off offset:2048
	global_load_dwordx4 v[56:59], v[26:27], off offset:3072
	global_load_dwordx4 v[62:65], v[78:79], off
	global_load_dwordx4 v[66:69], v[78:79], off offset:1024
	global_load_dwordx4 v[70:73], v[78:79], off offset:2048
	global_load_dwordx4 v[74:77], v[78:79], off offset:3072
	global_load_dwordx4 v[82:85], v[98:99], off
	global_load_dwordx4 v[86:89], v[98:99], off offset:1024
	global_load_dwordx4 v[90:93], v[98:99], off offset:2048
	global_load_dwordx4 v[94:97], v[98:99], off offset:3072
	v_lshl_add_u64 v[24:25], v[24:25], 0, s[12:13]
	v_lshl_add_u64 v[26:27], v[26:27], 0, s[12:13]
	v_lshl_add_u64 v[78:79], v[78:79], 0, s[12:13]
	v_lshl_add_u64 v[98:99], v[98:99], 0, s[12:13]
.Lslab_loop_an:
	s_cmp_eq_u32 s18, 1
	s_cbranch_scc1 .Lslab_lastA_an
	global_load_dwordx4 v[100:103], v[24:25], off
	global_load_dwordx4 v[104:107], v[24:25], off offset:1024
	global_load_dwordx4 v[108:111], v[24:25], off offset:2048
	global_load_dwordx4 v[112:115], v[24:25], off offset:3072
	global_load_dwordx4 v[116:119], v[26:27], off
	global_load_dwordx4 v[120:123], v[26:27], off offset:1024
	global_load_dwordx4 v[124:127], v[26:27], off offset:2048
	global_load_dwordx4 v[128:131], v[26:27], off offset:3072
	global_load_dwordx4 v[132:135], v[78:79], off
	global_load_dwordx4 v[136:139], v[78:79], off offset:1024
	global_load_dwordx4 v[140:143], v[78:79], off offset:2048
	global_load_dwordx4 v[144:147], v[78:79], off offset:3072
	global_load_dwordx4 v[164:167], v[98:99], off
	global_load_dwordx4 v[168:171], v[98:99], off offset:1024
	global_load_dwordx4 v[172:175], v[98:99], off offset:2048
	global_load_dwordx4 v[176:179], v[98:99], off offset:3072
	v_lshl_add_u64 v[24:25], v[24:25], 0, s[12:13]
	v_lshl_add_u64 v[26:27], v[26:27], 0, s[12:13]
	v_lshl_add_u64 v[78:79], v[78:79], 0, s[12:13]
	v_lshl_add_u64 v[98:99], v[98:99], 0, s[12:13]
	s_waitcnt vmcnt(28)
	v_pk_add_f32 v[8:9], v[8:9], v[28:29]
	v_pk_add_f32 v[10:11], v[10:11], v[30:31]
	v_pk_add_f32 v[12:13], v[12:13], v[32:33]
	v_pk_add_f32 v[14:15], v[14:15], v[34:35]
	v_pk_add_f32 v[16:17], v[16:17], v[36:37]
	v_pk_add_f32 v[18:19], v[18:19], v[38:39]
	v_pk_add_f32 v[20:21], v[20:21], v[40:41]
	v_pk_add_f32 v[22:23], v[22:23], v[42:43]
	s_waitcnt vmcnt(24)
	v_pk_add_f32 v[8:9], v[8:9], v[44:45]
	v_pk_add_f32 v[10:11], v[10:11], v[46:47]
	v_pk_add_f32 v[12:13], v[12:13], v[48:49]
	v_pk_add_f32 v[14:15], v[14:15], v[50:51]
	v_pk_add_f32 v[16:17], v[16:17], v[52:53]
	v_pk_add_f32 v[18:19], v[18:19], v[54:55]
	v_pk_add_f32 v[20:21], v[20:21], v[56:57]
	v_pk_add_f32 v[22:23], v[22:23], v[58:59]
	s_waitcnt vmcnt(20)
	v_pk_add_f32 v[8:9], v[8:9], v[62:63]
	v_pk_add_f32 v[10:11], v[10:11], v[64:65]
	v_pk_add_f32 v[12:13], v[12:13], v[66:67]
	v_pk_add_f32 v[14:15], v[14:15], v[68:69]
	v_pk_add_f32 v[16:17], v[16:17], v[70:71]
	v_pk_add_f32 v[18:19], v[18:19], v[72:73]
	v_pk_add_f32 v[20:21], v[20:21], v[74:75]
	v_pk_add_f32 v[22:23], v[22:23], v[76:77]
	s_waitcnt vmcnt(16)
	v_pk_add_f32 v[8:9], v[8:9], v[82:83]
	v_pk_add_f32 v[10:11], v[10:11], v[84:85]
	v_pk_add_f32 v[12:13], v[12:13], v[86:87]
	v_pk_add_f32 v[14:15], v[14:15], v[88:89]
	v_pk_add_f32 v[16:17], v[16:17], v[90:91]
	v_pk_add_f32 v[18:19], v[18:19], v[92:93]
	v_pk_add_f32 v[20:21], v[20:21], v[94:95]
	v_pk_add_f32 v[22:23], v[22:23], v[96:97]
	s_add_i32 s18, s18, -1
	s_cmp_eq_u32 s18, 1
	s_cbranch_scc1 .Lslab_lastB_an
	global_load_dwordx4 v[28:31], v[24:25], off
	global_load_dwordx4 v[32:35], v[24:25], off offset:1024
	global_load_dwordx4 v[36:39], v[24:25], off offset:2048
	global_load_dwordx4 v[40:43], v[24:25], off offset:3072
	global_load_dwordx4 v[44:47], v[26:27], off
	global_load_dwordx4 v[48:51], v[26:27], off offset:1024
	global_load_dwordx4 v[52:55], v[26:27], off offset:2048
	global_load_dwordx4 v[56:59], v[26:27], off offset:3072
	global_load_dwordx4 v[62:65], v[78:79], off
	global_load_dwordx4 v[66:69], v[78:79], off offset:1024
	global_load_dwordx4 v[70:73], v[78:79], off offset:2048
	global_load_dwordx4 v[74:77], v[78:79], off offset:3072
	global_load_dwordx4 v[82:85], v[98:99], off
	global_load_dwordx4 v[86:89], v[98:99], off offset:1024
	global_load_dwordx4 v[90:93], v[98:99], off offset:2048
	global_load_dwordx4 v[94:97], v[98:99], off offset:3072
	v_lshl_add_u64 v[24:25], v[24:25], 0, s[12:13]
	v_lshl_add_u64 v[26:27], v[26:27], 0, s[12:13]
	v_lshl_add_u64 v[78:79], v[78:79], 0, s[12:13]
	v_lshl_add_u64 v[98:99], v[98:99], 0, s[12:13]
	s_waitcnt vmcnt(28)
	v_pk_add_f32 v[8:9], v[8:9], v[100:101]
	v_pk_add_f32 v[10:11], v[10:11], v[102:103]
	v_pk_add_f32 v[12:13], v[12:13], v[104:105]
	v_pk_add_f32 v[14:15], v[14:15], v[106:107]
	v_pk_add_f32 v[16:17], v[16:17], v[108:109]
	v_pk_add_f32 v[18:19], v[18:19], v[110:111]
	v_pk_add_f32 v[20:21], v[20:21], v[112:113]
	v_pk_add_f32 v[22:23], v[22:23], v[114:115]
	s_waitcnt vmcnt(24)
	v_pk_add_f32 v[8:9], v[8:9], v[116:117]
	v_pk_add_f32 v[10:11], v[10:11], v[118:119]
	v_pk_add_f32 v[12:13], v[12:13], v[120:121]
	v_pk_add_f32 v[14:15], v[14:15], v[122:123]
	v_pk_add_f32 v[16:17], v[16:17], v[124:125]
	v_pk_add_f32 v[18:19], v[18:19], v[126:127]
	v_pk_add_f32 v[20:21], v[20:21], v[128:129]
	v_pk_add_f32 v[22:23], v[22:23], v[130:131]
	s_waitcnt vmcnt(20)
	v_pk_add_f32 v[8:9], v[8:9], v[132:133]
	v_pk_add_f32 v[10:11], v[10:11], v[134:135]
	v_pk_add_f32 v[12:13], v[12:13], v[136:137]
	v_pk_add_f32 v[14:15], v[14:15], v[138:139]
	v_pk_add_f32 v[16:17], v[16:17], v[140:141]
	v_pk_add_f32 v[18:19], v[18:19], v[142:143]
	v_pk_add_f32 v[20:21], v[20:21], v[144:145]
	v_pk_add_f32 v[22:23], v[22:23], v[146:147]
	s_waitcnt vmcnt(16)
	v_pk_add_f32 v[8:9], v[8:9], v[164:165]
	v_pk_add_f32 v[10:11], v[10:11], v[166:167]
	v_pk_add_f32 v[12:13], v[12:13], v[168:169]
	v_pk_add_f32 v[14:15], v[14:15], v[170:171]
	v_pk_add_f32 v[16:17], v[16:17], v[172:173]
	v_pk_add_f32 v[18:19], v[18:19], v[174:175]
	v_pk_add_f32 v[20:21], v[20:21], v[176:177]
	v_pk_add_f32 v[22:23], v[22:23], v[178:179]
	s_add_i32 s18, s18, -1
	s_branch .Lslab_loop_an
.Lslab_lastA_an:
	s_waitcnt vmcnt(12)
	v_pk_add_f32 v[8:9], v[8:9], v[28:29]
	v_pk_add_f32 v[10:11], v[10:11], v[30:31]
	v_pk_add_f32 v[12:13], v[12:13], v[32:33]
	v_pk_add_f32 v[14:15], v[14:15], v[34:35]
	v_pk_add_f32 v[16:17], v[16:17], v[36:37]
	v_pk_add_f32 v[18:19], v[18:19], v[38:39]
	v_pk_add_f32 v[20:21], v[20:21], v[40:41]
	v_pk_add_f32 v[22:23], v[22:23], v[42:43]
	s_waitcnt vmcnt(8)
	v_pk_add_f32 v[8:9], v[8:9], v[44:45]
	v_pk_add_f32 v[10:11], v[10:11], v[46:47]
	v_pk_add_f32 v[12:13], v[12:13], v[48:49]
	v_pk_add_f32 v[14:15], v[14:15], v[50:51]
	v_pk_add_f32 v[16:17], v[16:17], v[52:53]
	v_pk_add_f32 v[18:19], v[18:19], v[54:55]
	v_pk_add_f32 v[20:21], v[20:21], v[56:57]
	v_pk_add_f32 v[22:23], v[22:23], v[58:59]
	s_waitcnt vmcnt(4)
	v_pk_add_f32 v[8:9], v[8:9], v[62:63]
	v_pk_add_f32 v[10:11], v[10:11], v[64:65]
	v_pk_add_f32 v[12:13], v[12:13], v[66:67]
	v_pk_add_f32 v[14:15], v[14:15], v[68:69]
	v_pk_add_f32 v[16:17], v[16:17], v[70:71]
	v_pk_add_f32 v[18:19], v[18:19], v[72:73]
	v_pk_add_f32 v[20:21], v[20:21], v[74:75]
	v_pk_add_f32 v[22:23], v[22:23], v[76:77]
	s_waitcnt vmcnt(0)
	v_pk_add_f32 v[8:9], v[8:9], v[82:83]
	v_pk_add_f32 v[10:11], v[10:11], v[84:85]
	v_pk_add_f32 v[12:13], v[12:13], v[86:87]
	v_pk_add_f32 v[14:15], v[14:15], v[88:89]
	v_pk_add_f32 v[16:17], v[16:17], v[90:91]
	v_pk_add_f32 v[18:19], v[18:19], v[92:93]
	v_pk_add_f32 v[20:21], v[20:21], v[94:95]
	v_pk_add_f32 v[22:23], v[22:23], v[96:97]
	s_branch .Lslab_end_an
.Lslab_lastB_an:
	s_waitcnt vmcnt(12)
	v_pk_add_f32 v[8:9], v[8:9], v[100:101]
	v_pk_add_f32 v[10:11], v[10:11], v[102:103]
	v_pk_add_f32 v[12:13], v[12:13], v[104:105]
	v_pk_add_f32 v[14:15], v[14:15], v[106:107]
	v_pk_add_f32 v[16:17], v[16:17], v[108:109]
	v_pk_add_f32 v[18:19], v[18:19], v[110:111]
	v_pk_add_f32 v[20:21], v[20:21], v[112:113]
	v_pk_add_f32 v[22:23], v[22:23], v[114:115]
	s_waitcnt vmcnt(8)
	v_pk_add_f32 v[8:9], v[8:9], v[116:117]
	v_pk_add_f32 v[10:11], v[10:11], v[118:119]
	v_pk_add_f32 v[12:13], v[12:13], v[120:121]
	v_pk_add_f32 v[14:15], v[14:15], v[122:123]
	v_pk_add_f32 v[16:17], v[16:17], v[124:125]
	v_pk_add_f32 v[18:19], v[18:19], v[126:127]
	v_pk_add_f32 v[20:21], v[20:21], v[128:129]
	v_pk_add_f32 v[22:23], v[22:23], v[130:131]
	s_waitcnt vmcnt(4)
	v_pk_add_f32 v[8:9], v[8:9], v[132:133]
	v_pk_add_f32 v[10:11], v[10:11], v[134:135]
	v_pk_add_f32 v[12:13], v[12:13], v[136:137]
	v_pk_add_f32 v[14:15], v[14:15], v[138:139]
	v_pk_add_f32 v[16:17], v[16:17], v[140:141]
	v_pk_add_f32 v[18:19], v[18:19], v[142:143]
	v_pk_add_f32 v[20:21], v[20:21], v[144:145]
	v_pk_add_f32 v[22:23], v[22:23], v[146:147]
	s_waitcnt vmcnt(0)
	v_pk_add_f32 v[8:9], v[8:9], v[164:165]
	v_pk_add_f32 v[10:11], v[10:11], v[166:167]
	v_pk_add_f32 v[12:13], v[12:13], v[168:169]
	v_pk_add_f32 v[14:15], v[14:15], v[170:171]
	v_pk_add_f32 v[16:17], v[16:17], v[172:173]
	v_pk_add_f32 v[18:19], v[18:19], v[174:175]
	v_pk_add_f32 v[20:21], v[20:21], v[176:177]
	v_pk_add_f32 v[22:23], v[22:23], v[178:179]
.Lslab_end_an:
	v_readlane_b32 s14, v250, 15
	v_readlane_b32 s18, v250, 16
	s_add_u32 s12, s14, 0xb506000
	s_addc_u32 s13, s18, 0
	v_lshl_add_u64 v[4:5], s[12:13], 0, v[2:3]
	global_store_dwordx4 v[4:5], v[8:11], off
	global_store_dwordx4 v[4:5], v[12:15], off offset:1024
	global_store_dwordx4 v[4:5], v[16:19], off offset:2048
	global_store_dwordx4 v[4:5], v[20:23], off offset:3072
	s_branch .Lslab_done_a
.Lslab_a_l1:
	v_readlane_b32 s14, v250, 13
	v_readlane_b32 s18, v250, 14
	s_add_u32 s12, s14, 0x1000
	s_addc_u32 s13, s18, 0
	v_lshl_add_u64 v[4:5], s[12:13], 0, v[60:61]
	global_load_dwordx4 v[8:11], v[4:5], off sc1
	global_load_dwordx4 v[12:15], v[4:5], off offset:1024 sc1
	global_load_dwordx4 v[16:19], v[4:5], off offset:2048 sc1
	global_load_dwordx4 v[20:23], v[4:5], off offset:3072 sc1
	v_readlane_b32 s14, v250, 15
	v_readlane_b32 s18, v250, 16
	s_add_u32 s12, s14, 0x274e6000
	s_addc_u32 s13, s18, 0
	v_lshl_add_u64 v[24:25], s[12:13], 0, v[2:3]
	s_mov_b64 s[12:13], 0x100000
	v_lshl_add_u64 v[26:27], v[24:25], 0, s[12:13]
	v_lshl_add_u64 v[78:79], v[26:27], 0, s[12:13]
	v_lshl_add_u64 v[98:99], v[78:79], 0, s[12:13]
	s_mov_b64 s[12:13], 0x400000
	s_mov_b32 s18, 1
	global_load_dwordx4 v[28:31], v[24:25], off
	global_load_dwordx4 v[32:35], v[24:25], off offset:1024
	global_load_dwordx4 v[36:39], v[24:25], off offset:2048
	global_load_dwordx4 v[40:43], v[24:25], off offset:3072
	global_load_dwordx4 v[44:47], v[26:27], off
	global_load_dwordx4 v[48:51], v[26:27], off offset:1024
	global_load_dwordx4 v[52:55], v[26:27], off offset:2048
	global_load_dwordx4 v[56:59], v[26:27], off offset:3072
	global_load_dwordx4 v[62:65], v[78:79], off
	global_load_dwordx4 v[66:69], v[78:79], off offset:1024
	global_load_dwordx4 v[70:73], v[78:79], off offset:2048
	global_load_dwordx4 v[74:77], v[78:79], off offset:3072
	global_load_dwordx4 v[82:85], v[98:99], off
	global_load_dwordx4 v[86:89], v[98:99], off offset:1024
	global_load_dwordx4 v[90:93], v[98:99], off offset:2048
	global_load_dwordx4 v[94:97], v[98:99], off offset:3072
	v_lshl_add_u64 v[24:25], v[24:25], 0, s[12:13]
	v_lshl_add_u64 v[26:27], v[26:27], 0, s[12:13]
	v_lshl_add_u64 v[78:79], v[78:79], 0, s[12:13]
	v_lshl_add_u64 v[98:99], v[98:99], 0, s[12:13]

.Lslab_end_as:
	v_readlane_b32 s14, v250, 15
	v_readlane_b32 s18, v250, 16
	s_add_u32 s12, s14, 0xb506000
	s_addc_u32 s13, s18, 0
	v_lshl_add_u64 v[4:5], s[12:13], 0, v[2:3]
	global_store_dwordx4 v[4:5], v[8:11], off
	global_store_dwordx4 v[4:5], v[12:15], off offset:1024
	global_store_dwordx4 v[4:5], v[16:19], off offset:2048
	global_store_dwordx4 v[4:5], v[20:23], off offset:3072

.LBB0_3452:
	v_readlane_b32 s26, v250, 6
	s_cmp_gt_u32 s26, 0xff
	s_cbranch_scc1 .Lslab_skip_b
	v_and_b32_e32 v2, 63, v226
	v_lshlrev_b32_e32 v2, 4, v2
	v_lshl_add_u32 v60, s26, 13, v2
	v_mov_b32_e32 v61, 0
	v_lshl_add_u32 v2, s26, 12, v2
	v_mov_b32_e32 v3, 0
	v_readlane_b32 s27, v254, 55
	s_cmp_eq_u32 s27, 0
	s_cbranch_scc1 .Lslab_b_l0
	v_readlane_b32 s26, v250, 15
	v_readlane_b32 s27, v250, 16
	s_add_u32 s18, s26, 0xb506000
	s_addc_u32 s19, s27, 0
	v_lshl_add_u64 v[4:5], s[18:19], 0, v[2:3]
	global_load_dwordx4 v[8:11], v[4:5], off sc1
	global_load_dwordx4 v[12:15], v[4:5], off offset:1024 sc1
	global_load_dwordx4 v[16:19], v[4:5], off offset:2048 sc1
	global_load_dwordx4 v[20:23], v[4:5], off offset:3072 sc1
	v_readlane_b32 s26, v250, 15
	v_readlane_b32 s27, v250, 16
	s_add_u32 s18, s26, 0x274e6000
	s_addc_u32 s19, s27, 0
	v_lshl_add_u64 v[24:25], s[18:19], 0, v[2:3]
	s_mov_b64 s[18:19], 0x100000
	v_lshl_add_u64 v[26:27], v[24:25], 0, s[18:19]
	v_lshl_add_u64 v[78:79], v[26:27], 0, s[18:19]
	v_lshl_add_u64 v[98:99], v[78:79], 0, s[18:19]
	s_mov_b64 s[18:19], 0x400000
	s_mov_b32 s27, 4
	global_load_dwordx4 v[28:31], v[24:25], off
	global_load_dwordx4 v[32:35], v[24:25], off offset:1024
	global_load_dwordx4 v[36:39], v[24:25], off offset:2048
	global_load_dwordx4 v[40:43], v[24:25], off offset:3072
	global_load_dwordx4 v[44:47], v[26:27], off
	global_load_dwordx4 v[48:51], v[26:27], off offset:1024
	global_load_dwordx4 v[52:55], v[26:27], off offset:2048
	global_load_dwordx4 v[56:59], v[26:27], off offset:3072
	global_load_dwordx4 v[62:65], v[78:79], off
	global_load_dwordx4 v[66:69], v[78:79], off offset:1024
	global_load_dwordx4 v[70:73], v[78:79], off offset:2048
	global_load_dwordx4 v[74:77], v[78:79], off offset:3072
	global_load_dwordx4 v[82:85], v[98:99], off
	global_load_dwordx4 v[86:89], v[98:99], off offset:1024
	global_load_dwordx4 v[90:93], v[98:99], off offset:2048
	global_load_dwordx4 v[94:97], v[98:99], off offset:3072
	v_lshl_add_u64 v[24:25], v[24:25], 0, s[18:19]
	v_lshl_add_u64 v[26:27], v[26:27], 0, s[18:19]
	v_lshl_add_u64 v[78:79], v[78:79], 0, s[18:19]
	v_lshl_add_u64 v[98:99], v[98:99], 0, s[18:19]
.Lslab_loop_bn:
	s_cmp_eq_u32 s27, 1
	s_cbranch_scc1 .Lslab_lastA_bn
	global_load_dwordx4 v[100:103], v[24:25], off
	global_load_dwordx4 v[104:107], v[24:25], off offset:1024
	global_load_dwordx4 v[108:111], v[24:25], off offset:2048
	global_load_dwordx4 v[112:115], v[24:25], off offset:3072
	global_load_dwordx4 v[116:119], v[26:27], off
	global_load_dwordx4 v[120:123], v[26:27], off offset:1024
	global_load_dwordx4 v[124:127], v[26:27], off offset:2048
	global_load_dwordx4 v[128:131], v[26:27], off offset:3072
	global_load_dwordx4 v[132:135], v[78:79], off
	global_load_dwordx4 v[136:139], v[78:79], off offset:1024
	global_load_dwordx4 v[140:143], v[78:79], off offset:2048
	global_load_dwordx4 v[144:147], v[78:79], off offset:3072
	global_load_dwordx4 v[164:167], v[98:99], off
	global_load_dwordx4 v[168:171], v[98:99], off offset:1024
	global_load_dwordx4 v[172:175], v[98:99], off offset:2048
	global_load_dwordx4 v[176:179], v[98:99], off offset:3072
	v_lshl_add_u64 v[24:25], v[24:25], 0, s[18:19]
	v_lshl_add_u64 v[26:27], v[26:27], 0, s[18:19]
	v_lshl_add_u64 v[78:79], v[78:79], 0, s[18:19]
	v_lshl_add_u64 v[98:99], v[98:99], 0, s[18:19]
	s_waitcnt vmcnt(28)
	v_pk_add_f32 v[8:9], v[8:9], v[28:29]
	v_pk_add_f32 v[10:11], v[10:11], v[30:31]
	v_pk_add_f32 v[12:13], v[12:13], v[32:33]
	v_pk_add_f32 v[14:15], v[14:15], v[34:35]
	v_pk_add_f32 v[16:17], v[16:17], v[36:37]
	v_pk_add_f32 v[18:19], v[18:19], v[38:39]
	v_pk_add_f32 v[20:21], v[20:21], v[40:41]
	v_pk_add_f32 v[22:23], v[22:23], v[42:43]
	s_waitcnt vmcnt(24)
	v_pk_add_f32 v[8:9], v[8:9], v[44:45]
	v_pk_add_f32 v[10:11], v[10:11], v[46:47]
	v_pk_add_f32 v[12:13], v[12:13], v[48:49]
	v_pk_add_f32 v[14:15], v[14:15], v[50:51]
	v_pk_add_f32 v[16:17], v[16:17], v[52:53]
	v_pk_add_f32 v[18:19], v[18:19], v[54:55]
	v_pk_add_f32 v[20:21], v[20:21], v[56:57]
	v_pk_add_f32 v[22:23], v[22:23], v[58:59]
	s_waitcnt vmcnt(20)
	v_pk_add_f32 v[8:9], v[8:9], v[62:63]
	v_pk_add_f32 v[10:11], v[10:11], v[64:65]
	v_pk_add_f32 v[12:13], v[12:13], v[66:67]
	v_pk_add_f32 v[14:15], v[14:15], v[68:69]
	v_pk_add_f32 v[16:17], v[16:17], v[70:71]
	v_pk_add_f32 v[18:19], v[18:19], v[72:73]
	v_pk_add_f32 v[20:21], v[20:21], v[74:75]
	v_pk_add_f32 v[22:23], v[22:23], v[76:77]
	s_waitcnt vmcnt(16)
	v_pk_add_f32 v[8:9], v[8:9], v[82:83]
	v_pk_add_f32 v[10:11], v[10:11], v[84:85]
	v_pk_add_f32 v[12:13], v[12:13], v[86:87]
	v_pk_add_f32 v[14:15], v[14:15], v[88:89]
	v_pk_add_f32 v[16:17], v[16:17], v[90:91]
	v_pk_add_f32 v[18:19], v[18:19], v[92:93]
	v_pk_add_f32 v[20:21], v[20:21], v[94:95]
	v_pk_add_f32 v[22:23], v[22:23], v[96:97]
	s_add_i32 s27, s27, -1
	s_cmp_eq_u32 s27, 1
	s_cbranch_scc1 .Lslab_lastB_bn
	global_load_dwordx4 v[28:31], v[24:25], off
	global_load_dwordx4 v[32:35], v[24:25], off offset:1024
	global_load_dwordx4 v[36:39], v[24:25], off offset:2048
	global_load_dwordx4 v[40:43], v[24:25], off offset:3072
	global_load_dwordx4 v[44:47], v[26:27], off
	global_load_dwordx4 v[48:51], v[26:27], off offset:1024
	global_load_dwordx4 v[52:55], v[26:27], off offset:2048
	global_load_dwordx4 v[56:59], v[26:27], off offset:3072
	global_load_dwordx4 v[62:65], v[78:79], off
	global_load_dwordx4 v[66:69], v[78:79], off offset:1024
	global_load_dwordx4 v[70:73], v[78:79], off offset:2048
	global_load_dwordx4 v[74:77], v[78:79], off offset:3072
	global_load_dwordx4 v[82:85], v[98:99], off
	global_load_dwordx4 v[86:89], v[98:99], off offset:1024
	global_load_dwordx4 v[90:93], v[98:99], off offset:2048
	global_load_dwordx4 v[94:97], v[98:99], off offset:3072
	v_lshl_add_u64 v[24:25], v[24:25], 0, s[18:19]
	v_lshl_add_u64 v[26:27], v[26:27], 0, s[18:19]
	v_lshl_add_u64 v[78:79], v[78:79], 0, s[18:19]
	v_lshl_add_u64 v[98:99], v[98:99], 0, s[18:19]
	s_waitcnt vmcnt(28)
	v_pk_add_f32 v[8:9], v[8:9], v[100:101]
	v_pk_add_f32 v[10:11], v[10:11], v[102:103]
	v_pk_add_f32 v[12:13], v[12:13], v[104:105]
	v_pk_add_f32 v[14:15], v[14:15], v[106:107]
	v_pk_add_f32 v[16:17], v[16:17], v[108:109]
	v_pk_add_f32 v[18:19], v[18:19], v[110:111]
	v_pk_add_f32 v[20:21], v[20:21], v[112:113]
	v_pk_add_f32 v[22:23], v[22:23], v[114:115]
	s_waitcnt vmcnt(24)
	v_pk_add_f32 v[8:9], v[8:9], v[116:117]
	v_pk_add_f32 v[10:11], v[10:11], v[118:119]
	v_pk_add_f32 v[12:13], v[12:13], v[120:121]
	v_pk_add_f32 v[14:15], v[14:15], v[122:123]
	v_pk_add_f32 v[16:17], v[16:17], v[124:125]
	v_pk_add_f32 v[18:19], v[18:19], v[126:127]
	v_pk_add_f32 v[20:21], v[20:21], v[128:129]
	v_pk_add_f32 v[22:23], v[22:23], v[130:131]
	s_waitcnt vmcnt(20)
	v_pk_add_f32 v[8:9], v[8:9], v[132:133]
	v_pk_add_f32 v[10:11], v[10:11], v[134:135]
	v_pk_add_f32 v[12:13], v[12:13], v[136:137]
	v_pk_add_f32 v[14:15], v[14:15], v[138:139]
	v_pk_add_f32 v[16:17], v[16:17], v[140:141]
	v_pk_add_f32 v[18:19], v[18:19], v[142:143]
	v_pk_add_f32 v[20:21], v[20:21], v[144:145]
	v_pk_add_f32 v[22:23], v[22:23], v[146:147]
	s_waitcnt vmcnt(16)
	v_pk_add_f32 v[8:9], v[8:9], v[164:165]
	v_pk_add_f32 v[10:11], v[10:11], v[166:167]
	v_pk_add_f32 v[12:13], v[12:13], v[168:169]
	v_pk_add_f32 v[14:15], v[14:15], v[170:171]
	v_pk_add_f32 v[16:17], v[16:17], v[172:173]
	v_pk_add_f32 v[18:19], v[18:19], v[174:175]
	v_pk_add_f32 v[20:21], v[20:21], v[176:177]
	v_pk_add_f32 v[22:23], v[22:23], v[178:179]
	s_add_i32 s27, s27, -1
	s_branch .Lslab_loop_bn

.Lslab_end_bn:
	v_readlane_b32 s26, v250, 15
	v_readlane_b32 s27, v250, 16
	s_add_u32 s18, s26, 0xb506000
	s_addc_u32 s19, s27, 0
	v_lshl_add_u64 v[4:5], s[18:19], 0, v[2:3]
	global_store_dwordx4 v[4:5], v[8:11], off
	global_store_dwordx4 v[4:5], v[12:15], off offset:1024
	global_store_dwordx4 v[4:5], v[16:19], off offset:2048
	global_store_dwordx4 v[4:5], v[20:23], off offset:3072
	s_branch .Lslab_done_b
.Lslab_b_l0:
	v_readlane_b32 s26, v250, 15
	v_readlane_b32 s27, v250, 16
	s_add_u32 s18, s26, 0xb506000
	s_addc_u32 s19, s27, 0
	v_lshl_add_u64 v[4:5], s[18:19], 0, v[2:3]
	global_load_dwordx4 v[8:11], v[4:5], off sc1
	global_load_dwordx4 v[12:15], v[4:5], off offset:1024 sc1
	global_load_dwordx4 v[16:19], v[4:5], off offset:2048 sc1
	global_load_dwordx4 v[20:23], v[4:5], off offset:3072 sc1
	v_readlane_b32 s26, v250, 15
	v_readlane_b32 s27, v250, 16
	s_add_u32 s18, s26, 0x274e6000
	s_addc_u32 s19, s27, 0
	v_lshl_add_u64 v[24:25], s[18:19], 0, v[2:3]
	s_mov_b64 s[18:19], 0x100000
	v_lshl_add_u64 v[26:27], v[24:25], 0, s[18:19]
	v_lshl_add_u64 v[78:79], v[26:27], 0, s[18:19]
	v_lshl_add_u64 v[98:99], v[78:79], 0, s[18:19]
	s_mov_b64 s[18:19], 0x400000
	s_mov_b32 s27, 4
	global_load_dwordx4 v[28:31], v[24:25], off
	global_load_dwordx4 v[32:35], v[24:25], off offset:1024
	global_load_dwordx4 v[36:39], v[24:25], off offset:2048
	global_load_dwordx4 v[40:43], v[24:25], off offset:3072
	global_load_dwordx4 v[44:47], v[26:27], off
	global_load_dwordx4 v[48:51], v[26:27], off offset:1024
	global_load_dwordx4 v[52:55], v[26:27], off offset:2048
	global_load_dwordx4 v[56:59], v[26:27], off offset:3072
	global_load_dwordx4 v[62:65], v[78:79], off
	global_load_dwordx4 v[66:69], v[78:79], off offset:1024
	global_load_dwordx4 v[70:73], v[78:79], off offset:2048
	global_load_dwordx4 v[74:77], v[78:79], off offset:3072
	global_load_dwordx4 v[82:85], v[98:99], off
	global_load_dwordx4 v[86:89], v[98:99], off offset:1024
	global_load_dwordx4 v[90:93], v[98:99], off offset:2048
	global_load_dwordx4 v[94:97], v[98:99], off offset:3072
	v_lshl_add_u64 v[24:25], v[24:25], 0, s[18:19]
	v_lshl_add_u64 v[26:27], v[26:27], 0, s[18:19]
	v_lshl_add_u64 v[78:79], v[78:79], 0, s[18:19]
	v_lshl_add_u64 v[98:99], v[98:99], 0, s[18:19]

.Lslab_end_br1:
	v_readlane_b32 s26, v250, 13
	v_readlane_b32 s27, v250, 14
	s_add_u32 s18, s26, 0x1000
	s_addc_u32 s19, s27, 0
	v_lshl_add_u64 v[4:5], s[18:19], 0, v[60:61]
	global_store_dwordx4 v[4:5], v[8:11], off
	global_store_dwordx4 v[4:5], v[12:15], off offset:1024
	global_store_dwordx4 v[4:5], v[16:19], off offset:2048
	global_store_dwordx4 v[4:5], v[20:23], off offset:3072
	v_readlane_b32 s26, v250, 6
	s_cmp_gt_u32 s26, 0x7f
	s_cbranch_scc1 .Lslab_done_b
	s_cmp_eq_u32 s26, 0
	s_cbranch_scc1 .Lslab_b_row0plain
	v_readlane_b32 s26, v250, 15
	v_readlane_b32 s27, v250, 16
	s_add_u32 s18, s26, 0xb505000
	s_addc_u32 s19, s27, 0
	v_lshl_add_u64 v[4:5], s[18:19], 0, v[2:3]
	global_load_dwordx4 v[8:11], v[4:5], off sc1
	global_load_dwordx4 v[12:15], v[4:5], off offset:1024 sc1
	global_load_dwordx4 v[16:19], v[4:5], off offset:2048 sc1
	global_load_dwordx4 v[20:23], v[4:5], off offset:3072 sc1
	v_readlane_b32 s26, v250, 15
	v_readlane_b32 s27, v250, 16
	s_add_u32 s18, s26, 0x274e5000
	s_addc_u32 s19, s27, 0
	v_lshl_add_u64 v[24:25], s[18:19], 0, v[2:3]
	s_mov_b64 s[18:19], 0x100000
	v_lshl_add_u64 v[26:27], v[24:25], 0, s[18:19]
	v_lshl_add_u64 v[78:79], v[26:27], 0, s[18:19]
	v_lshl_add_u64 v[98:99], v[78:79], 0, s[18:19]
	s_mov_b64 s[18:19], 0x400000
	s_mov_b32 s27, 4
	global_load_dwordx4 v[28:31], v[24:25], off
	global_load_dwordx4 v[32:35], v[24:25], off offset:1024
	global_load_dwordx4 v[36:39], v[24:25], off offset:2048
	global_load_dwordx4 v[40:43], v[24:25], off offset:3072
	global_load_dwordx4 v[44:47], v[26:27], off
	global_load_dwordx4 v[48:51], v[26:27], off offset:1024
	global_load_dwordx4 v[52:55], v[26:27], off offset:2048
	global_load_dwordx4 v[56:59], v[26:27], off offset:3072
	global_load_dwordx4 v[62:65], v[78:79], off
	global_load_dwordx4 v[66:69], v[78:79], off offset:1024
	global_load_dwordx4 v[70:73], v[78:79], off offset:2048
	global_load_dwordx4 v[74:77], v[78:79], off offset:3072
	global_load_dwordx4 v[82:85], v[98:99], off
	global_load_dwordx4 v[86:89], v[98:99], off offset:1024
	global_load_dwordx4 v[90:93], v[98:99], off offset:2048
	global_load_dwordx4 v[94:97], v[98:99], off offset:3072
	v_lshl_add_u64 v[24:25], v[24:25], 0, s[18:19]
	v_lshl_add_u64 v[26:27], v[26:27], 0, s[18:19]
	v_lshl_add_u64 v[78:79], v[78:79], 0, s[18:19]
	v_lshl_add_u64 v[98:99], v[98:99], 0, s[18:19]

.Lslab_end_br0:
	v_readlane_b32 s26, v250, 13
	v_readlane_b32 s27, v250, 14
	s_add_u32 s18, s26, 0x0
	s_addc_u32 s19, s27, 0
	v_lshl_add_u64 v[4:5], s[18:19], 0, v[60:61]
	global_store_dwordx4 v[4:5], v[8:11], off
	global_store_dwordx4 v[4:5], v[12:15], off offset:1024
	global_store_dwordx4 v[4:5], v[16:19], off offset:2048
	global_store_dwordx4 v[4:5], v[20:23], off offset:3072
	s_branch .Lslab_done_b

.LBB0_4117:
	s_and_b64 vcc, exec, s[38:39]
	s_cbranch_vccz .LBB0_4106
	s_setprio 2
	v_lshl_add_u32 v104, v78, 2, s84
	ds_read_b128 v[20:23], v83 offset:4096
	ds_read_b128 v[16:19], v83 offset:0
	ds_read_b128 v[28:31], v83 offset:12288
	ds_read_b64 v[88:89], v104 offset:20480
	ds_read_b128 v[24:27], v83 offset:8192
	s_waitcnt lgkmcnt(4)
	v_pk_mul_f32 v[90:91], v[0:1], v[20:21] op_sel_hi:[1,0]
	v_pk_fma_f32 v[90:91], v[2:3], v[20:21], v[90:91] op_sel:[0,1,0]
	v_pk_fma_f32 v[90:91], v[4:5], v[22:23], v[90:91] op_sel_hi:[1,0,1]
	v_pk_fma_f32 v[90:91], v[6:7], v[22:23], v[90:91] op_sel:[0,1,0]
	ds_read_b128 v[20:23], v83 offset:4352
	ds_read_b128 v[84:87], v83 offset:16384
	v_add_f32_dpp v90, v90, v90 quad_perm:[1,0,3,2] row_mask:0xf bank_mask:0xf bound_ctrl:1
	v_add_f32_dpp v91, v91, v91 quad_perm:[1,0,3,2] row_mask:0xf bank_mask:0xf bound_ctrl:1
	s_nop 0
	v_add_f32_dpp v90, v90, v90 quad_perm:[2,3,0,1] row_mask:0xf bank_mask:0xf bound_ctrl:1
	v_add_f32_dpp v91, v91, v91 quad_perm:[2,3,0,1] row_mask:0xf bank_mask:0xf bound_ctrl:1
	s_nop 0
	v_add_f32_dpp v90, v90, v90 row_half_mirror row_mask:0xf bank_mask:0xf bound_ctrl:1
	v_add_f32_dpp v91, v91, v91 row_half_mirror row_mask:0xf bank_mask:0xf bound_ctrl:1
	s_nop 0
	v_add_f32_dpp v90, v90, v90 row_mirror row_mask:0xf bank_mask:0xf bound_ctrl:1
	v_add_f32_dpp v91, v91, v91 row_mirror row_mask:0xf bank_mask:0xf bound_ctrl:1
	s_waitcnt lgkmcnt(2)
	v_pk_mul_f32 v[0:1], v[0:1], v[16:17] op_sel_hi:[1,0]
	v_pk_mul_f32 v[2:3], v[2:3], v[16:17] op_sel:[0,1]
	v_pk_mul_f32 v[4:5], v[4:5], v[18:19] op_sel_hi:[1,0]
	v_pk_mul_f32 v[6:7], v[6:7], v[18:19] op_sel:[0,1]
	ds_read_b128 v[16:19], v83 offset:256
	v_pk_fma_f32 v[0:1], v[88:89], v[28:29], v[0:1] op_sel_hi:[1,0,1]
	v_pk_fma_f32 v[2:3], v[88:89], v[28:29], v[2:3] op_sel:[0,1,0]
	v_pk_fma_f32 v[4:5], v[88:89], v[30:31], v[4:5] op_sel_hi:[1,0,1]
	v_pk_fma_f32 v[6:7], v[88:89], v[30:31], v[6:7] op_sel:[0,1,0]
	ds_read_b128 v[28:31], v83 offset:12544
	ds_read_b64 v[88:89], v104 offset:20736
	v_pk_fma_f32 v[0:1], v[90:91], v[24:25], v[0:1] op_sel_hi:[1,0,1] neg_lo:[1,0,0] neg_hi:[1,0,0]
	v_pk_fma_f32 v[2:3], v[90:91], v[24:25], v[2:3] op_sel:[0,1,0] neg_lo:[1,0,0] neg_hi:[1,0,0]
	v_pk_fma_f32 v[4:5], v[90:91], v[26:27], v[4:5] op_sel_hi:[1,0,1] neg_lo:[1,0,0] neg_hi:[1,0,0]
	v_pk_fma_f32 v[6:7], v[90:91], v[26:27], v[6:7] op_sel:[0,1,0] neg_lo:[1,0,0] neg_hi:[1,0,0]
	ds_read_b128 v[24:27], v83 offset:8448
	s_waitcnt lgkmcnt(4)
	v_pk_mul_f32 v[90:91], v[0:1], v[20:21] op_sel_hi:[1,0]
	v_pk_mul_f32 v[92:93], v[0:1], v[84:85] op_sel_hi:[1,0]
	v_pk_fma_f32 v[90:91], v[2:3], v[20:21], v[90:91] op_sel:[0,1,0]
	v_pk_fma_f32 v[92:93], v[2:3], v[84:85], v[92:93] op_sel:[0,1,0]
	v_pk_fma_f32 v[90:91], v[4:5], v[22:23], v[90:91] op_sel_hi:[1,0,1]
	v_pk_fma_f32 v[92:93], v[4:5], v[86:87], v[92:93] op_sel_hi:[1,0,1]
	v_pk_fma_f32 v[90:91], v[6:7], v[22:23], v[90:91] op_sel:[0,1,0]
	v_pk_fma_f32 v[8:9], v[6:7], v[86:87], v[92:93] op_sel:[0,1,0]
	ds_read_b128 v[20:23], v83 offset:4608
	ds_read_b128 v[84:87], v83 offset:16640
	v_add_f32_dpp v90, v90, v90 quad_perm:[1,0,3,2] row_mask:0xf bank_mask:0xf bound_ctrl:1
	v_add_f32_dpp v91, v91, v91 quad_perm:[1,0,3,2] row_mask:0xf bank_mask:0xf bound_ctrl:1
	s_nop 0
	v_add_f32_dpp v90, v90, v90 quad_perm:[2,3,0,1] row_mask:0xf bank_mask:0xf bound_ctrl:1
	v_add_f32_dpp v91, v91, v91 quad_perm:[2,3,0,1] row_mask:0xf bank_mask:0xf bound_ctrl:1
	s_nop 0
	v_add_f32_dpp v90, v90, v90 row_half_mirror row_mask:0xf bank_mask:0xf bound_ctrl:1
	v_add_f32_dpp v91, v91, v91 row_half_mirror row_mask:0xf bank_mask:0xf bound_ctrl:1
	s_nop 0
	v_add_f32_dpp v90, v90, v90 row_mirror row_mask:0xf bank_mask:0xf bound_ctrl:1
	v_add_f32_dpp v91, v91, v91 row_mirror row_mask:0xf bank_mask:0xf bound_ctrl:1
	s_waitcnt lgkmcnt(2)
	v_pk_mul_f32 v[0:1], v[0:1], v[16:17] op_sel_hi:[1,0]
	v_pk_mul_f32 v[2:3], v[2:3], v[16:17] op_sel:[0,1]
	v_pk_mul_f32 v[4:5], v[4:5], v[18:19] op_sel_hi:[1,0]
	v_pk_mul_f32 v[6:7], v[6:7], v[18:19] op_sel:[0,1]
	ds_read_b128 v[16:19], v83 offset:512
	v_pk_fma_f32 v[0:1], v[88:89], v[28:29], v[0:1] op_sel_hi:[1,0,1]
	v_pk_fma_f32 v[2:3], v[88:89], v[28:29], v[2:3] op_sel:[0,1,0]
	v_pk_fma_f32 v[4:5], v[88:89], v[30:31], v[4:5] op_sel_hi:[1,0,1]
	v_pk_fma_f32 v[6:7], v[88:89], v[30:31], v[6:7] op_sel:[0,1,0]
	ds_read_b128 v[28:31], v83 offset:12800
	ds_read_b64 v[88:89], v104 offset:20992
	v_pk_fma_f32 v[0:1], v[90:91], v[24:25], v[0:1] op_sel_hi:[1,0,1] neg_lo:[1,0,0] neg_hi:[1,0,0]
	v_pk_fma_f32 v[2:3], v[90:91], v[24:25], v[2:3] op_sel:[0,1,0] neg_lo:[1,0,0] neg_hi:[1,0,0]
	v_pk_fma_f32 v[4:5], v[90:91], v[26:27], v[4:5] op_sel_hi:[1,0,1] neg_lo:[1,0,0] neg_hi:[1,0,0]
	v_pk_fma_f32 v[6:7], v[90:91], v[26:27], v[6:7] op_sel:[0,1,0] neg_lo:[1,0,0] neg_hi:[1,0,0]
	ds_read_b128 v[24:27], v83 offset:8704
	s_waitcnt lgkmcnt(4)
	v_pk_mul_f32 v[90:91], v[0:1], v[20:21] op_sel_hi:[1,0]
	v_pk_mul_f32 v[92:93], v[0:1], v[84:85] op_sel_hi:[1,0]
	v_pk_fma_f32 v[90:91], v[2:3], v[20:21], v[90:91] op_sel:[0,1,0]
	v_pk_fma_f32 v[92:93], v[2:3], v[84:85], v[92:93] op_sel:[0,1,0]
	v_pk_fma_f32 v[90:91], v[4:5], v[22:23], v[90:91] op_sel_hi:[1,0,1]
	v_pk_fma_f32 v[92:93], v[4:5], v[86:87], v[92:93] op_sel_hi:[1,0,1]
	v_pk_fma_f32 v[90:91], v[6:7], v[22:23], v[90:91] op_sel:[0,1,0]
	v_pk_fma_f32 v[10:11], v[6:7], v[86:87], v[92:93] op_sel:[0,1,0]
	ds_read_b128 v[20:23], v83 offset:4864
	ds_read_b128 v[84:87], v83 offset:16896
	v_add_f32_dpp v90, v90, v90 quad_perm:[1,0,3,2] row_mask:0xf bank_mask:0xf bound_ctrl:1
	v_add_f32_dpp v91, v91, v91 quad_perm:[1,0,3,2] row_mask:0xf bank_mask:0xf bound_ctrl:1
	v_add_f32_dpp v8, v8, v8 row_mirror row_mask:0xf bank_mask:0x3
	v_add_f32_dpp v90, v90, v90 quad_perm:[2,3,0,1] row_mask:0xf bank_mask:0xf bound_ctrl:1
	v_add_f32_dpp v91, v91, v91 quad_perm:[2,3,0,1] row_mask:0xf bank_mask:0xf bound_ctrl:1
	v_add_f32_dpp v9, v9, v9 row_mirror row_mask:0xf bank_mask:0x3
	v_add_f32_dpp v90, v90, v90 row_half_mirror row_mask:0xf bank_mask:0xf bound_ctrl:1
	v_add_f32_dpp v91, v91, v91 row_half_mirror row_mask:0xf bank_mask:0xf bound_ctrl:1
	v_add_f32_dpp v8, v10, v10 row_mirror row_mask:0xf bank_mask:0xc
	v_add_f32_dpp v90, v90, v90 row_mirror row_mask:0xf bank_mask:0xf bound_ctrl:1
	v_add_f32_dpp v91, v91, v91 row_mirror row_mask:0xf bank_mask:0xf bound_ctrl:1
	s_waitcnt lgkmcnt(2)
	v_pk_mul_f32 v[0:1], v[0:1], v[16:17] op_sel_hi:[1,0]
	v_pk_mul_f32 v[2:3], v[2:3], v[16:17] op_sel:[0,1]
	v_pk_mul_f32 v[4:5], v[4:5], v[18:19] op_sel_hi:[1,0]
	v_pk_mul_f32 v[6:7], v[6:7], v[18:19] op_sel:[0,1]
	ds_read_b128 v[16:19], v83 offset:768
	v_pk_fma_f32 v[0:1], v[88:89], v[28:29], v[0:1] op_sel_hi:[1,0,1]
	v_pk_fma_f32 v[2:3], v[88:89], v[28:29], v[2:3] op_sel:[0,1,0]
	v_pk_fma_f32 v[4:5], v[88:89], v[30:31], v[4:5] op_sel_hi:[1,0,1]
	v_pk_fma_f32 v[6:7], v[88:89], v[30:31], v[6:7] op_sel:[0,1,0]
	ds_read_b128 v[28:31], v83 offset:13056
	ds_read_b64 v[88:89], v104 offset:21248
	v_pk_fma_f32 v[0:1], v[90:91], v[24:25], v[0:1] op_sel_hi:[1,0,1] neg_lo:[1,0,0] neg_hi:[1,0,0]
	v_pk_fma_f32 v[2:3], v[90:91], v[24:25], v[2:3] op_sel:[0,1,0] neg_lo:[1,0,0] neg_hi:[1,0,0]
	v_pk_fma_f32 v[4:5], v[90:91], v[26:27], v[4:5] op_sel_hi:[1,0,1] neg_lo:[1,0,0] neg_hi:[1,0,0]
	v_pk_fma_f32 v[6:7], v[90:91], v[26:27], v[6:7] op_sel:[0,1,0] neg_lo:[1,0,0] neg_hi:[1,0,0]
	ds_read_b128 v[24:27], v83 offset:8960
	v_add_f32_dpp v9, v11, v11 row_mirror row_mask:0xf bank_mask:0xc
	s_waitcnt lgkmcnt(4)
	v_pk_mul_f32 v[90:91], v[0:1], v[20:21] op_sel_hi:[1,0]
	v_pk_mul_f32 v[92:93], v[0:1], v[84:85] op_sel_hi:[1,0]
	v_pk_fma_f32 v[90:91], v[2:3], v[20:21], v[90:91] op_sel:[0,1,0]
	v_pk_fma_f32 v[92:93], v[2:3], v[84:85], v[92:93] op_sel:[0,1,0]
	v_pk_fma_f32 v[90:91], v[4:5], v[22:23], v[90:91] op_sel_hi:[1,0,1]
	v_pk_fma_f32 v[92:93], v[4:5], v[86:87], v[92:93] op_sel_hi:[1,0,1]
	v_pk_fma_f32 v[90:91], v[6:7], v[22:23], v[90:91] op_sel:[0,1,0]
	v_pk_fma_f32 v[12:13], v[6:7], v[86:87], v[92:93] op_sel:[0,1,0]
	ds_read_b128 v[20:23], v83 offset:5120
	ds_read_b128 v[84:87], v83 offset:17152
	v_add_f32_dpp v90, v90, v90 quad_perm:[1,0,3,2] row_mask:0xf bank_mask:0xf bound_ctrl:1
	v_add_f32_dpp v91, v91, v91 quad_perm:[1,0,3,2] row_mask:0xf bank_mask:0xf bound_ctrl:1
	s_nop 0
	v_add_f32_dpp v90, v90, v90 quad_perm:[2,3,0,1] row_mask:0xf bank_mask:0xf bound_ctrl:1
	v_add_f32_dpp v91, v91, v91 quad_perm:[2,3,0,1] row_mask:0xf bank_mask:0xf bound_ctrl:1
	s_nop 0
	v_add_f32_dpp v90, v90, v90 row_half_mirror row_mask:0xf bank_mask:0xf bound_ctrl:1
	v_add_f32_dpp v91, v91, v91 row_half_mirror row_mask:0xf bank_mask:0xf bound_ctrl:1
	s_nop 0
	v_add_f32_dpp v90, v90, v90 row_mirror row_mask:0xf bank_mask:0xf bound_ctrl:1
	v_add_f32_dpp v91, v91, v91 row_mirror row_mask:0xf bank_mask:0xf bound_ctrl:1
	s_waitcnt lgkmcnt(2)
	v_pk_mul_f32 v[0:1], v[0:1], v[16:17] op_sel_hi:[1,0]
	v_pk_mul_f32 v[2:3], v[2:3], v[16:17] op_sel:[0,1]
	v_pk_mul_f32 v[4:5], v[4:5], v[18:19] op_sel_hi:[1,0]
	v_pk_mul_f32 v[6:7], v[6:7], v[18:19] op_sel:[0,1]
	ds_read_b128 v[16:19], v83 offset:1024
	v_pk_fma_f32 v[0:1], v[88:89], v[28:29], v[0:1] op_sel_hi:[1,0,1]
	v_pk_fma_f32 v[2:3], v[88:89], v[28:29], v[2:3] op_sel:[0,1,0]
	v_pk_fma_f32 v[4:5], v[88:89], v[30:31], v[4:5] op_sel_hi:[1,0,1]
	v_pk_fma_f32 v[6:7], v[88:89], v[30:31], v[6:7] op_sel:[0,1,0]
	ds_read_b128 v[28:31], v83 offset:13312
	ds_read_b64 v[88:89], v104 offset:21504
	v_pk_fma_f32 v[0:1], v[90:91], v[24:25], v[0:1] op_sel_hi:[1,0,1] neg_lo:[1,0,0] neg_hi:[1,0,0]
	v_pk_fma_f32 v[2:3], v[90:91], v[24:25], v[2:3] op_sel:[0,1,0] neg_lo:[1,0,0] neg_hi:[1,0,0]
	v_pk_fma_f32 v[4:5], v[90:91], v[26:27], v[4:5] op_sel_hi:[1,0,1] neg_lo:[1,0,0] neg_hi:[1,0,0]
	v_pk_fma_f32 v[6:7], v[90:91], v[26:27], v[6:7] op_sel:[0,1,0] neg_lo:[1,0,0] neg_hi:[1,0,0]
	ds_read_b128 v[24:27], v83 offset:9216
	s_waitcnt lgkmcnt(4)
	v_pk_mul_f32 v[90:91], v[0:1], v[20:21] op_sel_hi:[1,0]
	v_pk_mul_f32 v[92:93], v[0:1], v[84:85] op_sel_hi:[1,0]
	v_pk_fma_f32 v[90:91], v[2:3], v[20:21], v[90:91] op_sel:[0,1,0]
	v_pk_fma_f32 v[92:93], v[2:3], v[84:85], v[92:93] op_sel:[0,1,0]
	v_pk_fma_f32 v[90:91], v[4:5], v[22:23], v[90:91] op_sel_hi:[1,0,1]
	v_pk_fma_f32 v[92:93], v[4:5], v[86:87], v[92:93] op_sel_hi:[1,0,1]
	v_pk_fma_f32 v[90:91], v[6:7], v[22:23], v[90:91] op_sel:[0,1,0]
	v_pk_fma_f32 v[14:15], v[6:7], v[86:87], v[92:93] op_sel:[0,1,0]
	ds_read_b128 v[20:23], v83 offset:5376
	ds_read_b128 v[84:87], v83 offset:17408
	v_add_f32_dpp v90, v90, v90 quad_perm:[1,0,3,2] row_mask:0xf bank_mask:0xf bound_ctrl:1
	v_add_f32_dpp v91, v91, v91 quad_perm:[1,0,3,2] row_mask:0xf bank_mask:0xf bound_ctrl:1
	v_add_f32_dpp v12, v12, v12 row_mirror row_mask:0xf bank_mask:0x3
	v_add_f32_dpp v90, v90, v90 quad_perm:[2,3,0,1] row_mask:0xf bank_mask:0xf bound_ctrl:1
	v_add_f32_dpp v91, v91, v91 quad_perm:[2,3,0,1] row_mask:0xf bank_mask:0xf bound_ctrl:1
	v_add_f32_dpp v13, v13, v13 row_mirror row_mask:0xf bank_mask:0x3
	v_add_f32_dpp v90, v90, v90 row_half_mirror row_mask:0xf bank_mask:0xf bound_ctrl:1
	v_add_f32_dpp v91, v91, v91 row_half_mirror row_mask:0xf bank_mask:0xf bound_ctrl:1
	v_add_f32_dpp v12, v14, v14 row_mirror row_mask:0xf bank_mask:0xc
	v_add_f32_dpp v90, v90, v90 row_mirror row_mask:0xf bank_mask:0xf bound_ctrl:1
	v_add_f32_dpp v91, v91, v91 row_mirror row_mask:0xf bank_mask:0xf bound_ctrl:1
	s_waitcnt lgkmcnt(2)
	v_pk_mul_f32 v[0:1], v[0:1], v[16:17] op_sel_hi:[1,0]
	v_pk_mul_f32 v[2:3], v[2:3], v[16:17] op_sel:[0,1]
	v_pk_mul_f32 v[4:5], v[4:5], v[18:19] op_sel_hi:[1,0]
	v_pk_mul_f32 v[6:7], v[6:7], v[18:19] op_sel:[0,1]
	ds_read_b128 v[16:19], v83 offset:1280
	v_pk_fma_f32 v[0:1], v[88:89], v[28:29], v[0:1] op_sel_hi:[1,0,1]
	v_pk_fma_f32 v[2:3], v[88:89], v[28:29], v[2:3] op_sel:[0,1,0]
	v_pk_fma_f32 v[4:5], v[88:89], v[30:31], v[4:5] op_sel_hi:[1,0,1]
	v_pk_fma_f32 v[6:7], v[88:89], v[30:31], v[6:7] op_sel:[0,1,0]
	ds_read_b128 v[28:31], v83 offset:13568
	ds_read_b64 v[88:89], v104 offset:21760
	v_pk_fma_f32 v[0:1], v[90:91], v[24:25], v[0:1] op_sel_hi:[1,0,1] neg_lo:[1,0,0] neg_hi:[1,0,0]
	v_pk_fma_f32 v[2:3], v[90:91], v[24:25], v[2:3] op_sel:[0,1,0] neg_lo:[1,0,0] neg_hi:[1,0,0]
	v_pk_fma_f32 v[4:5], v[90:91], v[26:27], v[4:5] op_sel_hi:[1,0,1] neg_lo:[1,0,0] neg_hi:[1,0,0]
	v_pk_fma_f32 v[6:7], v[90:91], v[26:27], v[6:7] op_sel:[0,1,0] neg_lo:[1,0,0] neg_hi:[1,0,0]
	ds_read_b128 v[24:27], v83 offset:9472
	v_add_f32_dpp v13, v15, v15 row_mirror row_mask:0xf bank_mask:0xc
	s_waitcnt lgkmcnt(4)
	v_pk_mul_f32 v[90:91], v[0:1], v[20:21] op_sel_hi:[1,0]
	v_pk_mul_f32 v[92:93], v[0:1], v[84:85] op_sel_hi:[1,0]
	v_pk_fma_f32 v[90:91], v[2:3], v[20:21], v[90:91] op_sel:[0,1,0]
	v_pk_fma_f32 v[92:93], v[2:3], v[84:85], v[92:93] op_sel:[0,1,0]
	v_pk_fma_f32 v[90:91], v[4:5], v[22:23], v[90:91] op_sel_hi:[1,0,1]
	v_pk_fma_f32 v[92:93], v[4:5], v[86:87], v[92:93] op_sel_hi:[1,0,1]
	v_pk_fma_f32 v[90:91], v[6:7], v[22:23], v[90:91] op_sel:[0,1,0]
	v_pk_fma_f32 v[70:71], v[6:7], v[86:87], v[92:93] op_sel:[0,1,0]
	ds_read_b128 v[20:23], v83 offset:5632
	ds_read_b128 v[84:87], v83 offset:17664
	v_add_f32_dpp v90, v90, v90 quad_perm:[1,0,3,2] row_mask:0xf bank_mask:0xf bound_ctrl:1
	v_add_f32_dpp v91, v91, v91 quad_perm:[1,0,3,2] row_mask:0xf bank_mask:0xf bound_ctrl:1
	v_add_f32_dpp v8, v8, v8 row_half_mirror row_mask:0xf bank_mask:0x5
	v_add_f32_dpp v90, v90, v90 quad_perm:[2,3,0,1] row_mask:0xf bank_mask:0xf bound_ctrl:1
	v_add_f32_dpp v91, v91, v91 quad_perm:[2,3,0,1] row_mask:0xf bank_mask:0xf bound_ctrl:1
	v_add_f32_dpp v9, v9, v9 row_half_mirror row_mask:0xf bank_mask:0x5
	v_add_f32_dpp v90, v90, v90 row_half_mirror row_mask:0xf bank_mask:0xf bound_ctrl:1
	v_add_f32_dpp v91, v91, v91 row_half_mirror row_mask:0xf bank_mask:0xf bound_ctrl:1
	v_add_f32_dpp v8, v12, v12 row_half_mirror row_mask:0xf bank_mask:0xa
	v_add_f32_dpp v90, v90, v90 row_mirror row_mask:0xf bank_mask:0xf bound_ctrl:1
	v_add_f32_dpp v91, v91, v91 row_mirror row_mask:0xf bank_mask:0xf bound_ctrl:1
	s_waitcnt lgkmcnt(2)
	v_pk_mul_f32 v[0:1], v[0:1], v[16:17] op_sel_hi:[1,0]
	v_pk_mul_f32 v[2:3], v[2:3], v[16:17] op_sel:[0,1]
	v_pk_mul_f32 v[4:5], v[4:5], v[18:19] op_sel_hi:[1,0]
	v_pk_mul_f32 v[6:7], v[6:7], v[18:19] op_sel:[0,1]
	ds_read_b128 v[16:19], v83 offset:1536
	v_pk_fma_f32 v[0:1], v[88:89], v[28:29], v[0:1] op_sel_hi:[1,0,1]
	v_pk_fma_f32 v[2:3], v[88:89], v[28:29], v[2:3] op_sel:[0,1,0]
	v_pk_fma_f32 v[4:5], v[88:89], v[30:31], v[4:5] op_sel_hi:[1,0,1]
	v_pk_fma_f32 v[6:7], v[88:89], v[30:31], v[6:7] op_sel:[0,1,0]
	ds_read_b128 v[28:31], v83 offset:13824
	ds_read_b64 v[88:89], v104 offset:22016
	v_pk_fma_f32 v[0:1], v[90:91], v[24:25], v[0:1] op_sel_hi:[1,0,1] neg_lo:[1,0,0] neg_hi:[1,0,0]
	v_pk_fma_f32 v[2:3], v[90:91], v[24:25], v[2:3] op_sel:[0,1,0] neg_lo:[1,0,0] neg_hi:[1,0,0]
	v_pk_fma_f32 v[4:5], v[90:91], v[26:27], v[4:5] op_sel_hi:[1,0,1] neg_lo:[1,0,0] neg_hi:[1,0,0]
	v_pk_fma_f32 v[6:7], v[90:91], v[26:27], v[6:7] op_sel:[0,1,0] neg_lo:[1,0,0] neg_hi:[1,0,0]
	ds_read_b128 v[24:27], v83 offset:9728
	v_add_f32_dpp v9, v13, v13 row_half_mirror row_mask:0xf bank_mask:0xa
	s_waitcnt lgkmcnt(4)
	v_pk_mul_f32 v[90:91], v[0:1], v[20:21] op_sel_hi:[1,0]
	v_pk_mul_f32 v[92:93], v[0:1], v[84:85] op_sel_hi:[1,0]
	v_pk_fma_f32 v[90:91], v[2:3], v[20:21], v[90:91] op_sel:[0,1,0]
	v_pk_fma_f32 v[92:93], v[2:3], v[84:85], v[92:93] op_sel:[0,1,0]
	v_pk_fma_f32 v[90:91], v[4:5], v[22:23], v[90:91] op_sel_hi:[1,0,1]
	v_pk_fma_f32 v[92:93], v[4:5], v[86:87], v[92:93] op_sel_hi:[1,0,1]
	v_pk_fma_f32 v[90:91], v[6:7], v[22:23], v[90:91] op_sel:[0,1,0]
	v_pk_fma_f32 v[72:73], v[6:7], v[86:87], v[92:93] op_sel:[0,1,0]
	ds_read_b128 v[20:23], v83 offset:5888
	ds_read_b128 v[84:87], v83 offset:17920
	v_add_f32_dpp v90, v90, v90 quad_perm:[1,0,3,2] row_mask:0xf bank_mask:0xf bound_ctrl:1
	v_add_f32_dpp v91, v91, v91 quad_perm:[1,0,3,2] row_mask:0xf bank_mask:0xf bound_ctrl:1
	v_add_f32_dpp v70, v70, v70 row_mirror row_mask:0xf bank_mask:0x3
	v_add_f32_dpp v90, v90, v90 quad_perm:[2,3,0,1] row_mask:0xf bank_mask:0xf bound_ctrl:1
	v_add_f32_dpp v91, v91, v91 quad_perm:[2,3,0,1] row_mask:0xf bank_mask:0xf bound_ctrl:1
	v_add_f32_dpp v71, v71, v71 row_mirror row_mask:0xf bank_mask:0x3
	v_add_f32_dpp v90, v90, v90 row_half_mirror row_mask:0xf bank_mask:0xf bound_ctrl:1
	v_add_f32_dpp v91, v91, v91 row_half_mirror row_mask:0xf bank_mask:0xf bound_ctrl:1
	v_add_f32_dpp v70, v72, v72 row_mirror row_mask:0xf bank_mask:0xc
	v_add_f32_dpp v90, v90, v90 row_mirror row_mask:0xf bank_mask:0xf bound_ctrl:1
	v_add_f32_dpp v91, v91, v91 row_mirror row_mask:0xf bank_mask:0xf bound_ctrl:1
	s_waitcnt lgkmcnt(2)
	v_pk_mul_f32 v[0:1], v[0:1], v[16:17] op_sel_hi:[1,0]
	v_pk_mul_f32 v[2:3], v[2:3], v[16:17] op_sel:[0,1]
	v_pk_mul_f32 v[4:5], v[4:5], v[18:19] op_sel_hi:[1,0]
	v_pk_mul_f32 v[6:7], v[6:7], v[18:19] op_sel:[0,1]
	ds_read_b128 v[16:19], v83 offset:1792
	v_pk_fma_f32 v[0:1], v[88:89], v[28:29], v[0:1] op_sel_hi:[1,0,1]
	v_pk_fma_f32 v[2:3], v[88:89], v[28:29], v[2:3] op_sel:[0,1,0]
	v_pk_fma_f32 v[4:5], v[88:89], v[30:31], v[4:5] op_sel_hi:[1,0,1]
	v_pk_fma_f32 v[6:7], v[88:89], v[30:31], v[6:7] op_sel:[0,1,0]
	ds_read_b128 v[28:31], v83 offset:14080
	ds_read_b64 v[88:89], v104 offset:22272
	v_pk_fma_f32 v[0:1], v[90:91], v[24:25], v[0:1] op_sel_hi:[1,0,1] neg_lo:[1,0,0] neg_hi:[1,0,0]
	v_pk_fma_f32 v[2:3], v[90:91], v[24:25], v[2:3] op_sel:[0,1,0] neg_lo:[1,0,0] neg_hi:[1,0,0]
	v_pk_fma_f32 v[4:5], v[90:91], v[26:27], v[4:5] op_sel_hi:[1,0,1] neg_lo:[1,0,0] neg_hi:[1,0,0]
	v_pk_fma_f32 v[6:7], v[90:91], v[26:27], v[6:7] op_sel:[0,1,0] neg_lo:[1,0,0] neg_hi:[1,0,0]
	ds_read_b128 v[24:27], v83 offset:9984
	v_add_f32_dpp v71, v73, v73 row_mirror row_mask:0xf bank_mask:0xc
	s_waitcnt lgkmcnt(4)
	v_pk_mul_f32 v[90:91], v[0:1], v[20:21] op_sel_hi:[1,0]
	v_pk_mul_f32 v[92:93], v[0:1], v[84:85] op_sel_hi:[1,0]
	v_pk_fma_f32 v[90:91], v[2:3], v[20:21], v[90:91] op_sel:[0,1,0]
	v_pk_fma_f32 v[92:93], v[2:3], v[84:85], v[92:93] op_sel:[0,1,0]
	v_pk_fma_f32 v[90:91], v[4:5], v[22:23], v[90:91] op_sel_hi:[1,0,1]
	v_pk_fma_f32 v[92:93], v[4:5], v[86:87], v[92:93] op_sel_hi:[1,0,1]
	v_pk_fma_f32 v[90:91], v[6:7], v[22:23], v[90:91] op_sel:[0,1,0]
	v_pk_fma_f32 v[94:95], v[6:7], v[86:87], v[92:93] op_sel:[0,1,0]
	ds_read_b128 v[20:23], v83 offset:6144
	ds_read_b128 v[84:87], v83 offset:18176
	v_add_f32_dpp v90, v90, v90 quad_perm:[1,0,3,2] row_mask:0xf bank_mask:0xf bound_ctrl:1
	v_add_f32_dpp v91, v91, v91 quad_perm:[1,0,3,2] row_mask:0xf bank_mask:0xf bound_ctrl:1
	s_nop 0
	v_add_f32_dpp v90, v90, v90 quad_perm:[2,3,0,1] row_mask:0xf bank_mask:0xf bound_ctrl:1
	v_add_f32_dpp v91, v91, v91 quad_perm:[2,3,0,1] row_mask:0xf bank_mask:0xf bound_ctrl:1
	s_nop 0
	v_add_f32_dpp v90, v90, v90 row_half_mirror row_mask:0xf bank_mask:0xf bound_ctrl:1
	v_add_f32_dpp v91, v91, v91 row_half_mirror row_mask:0xf bank_mask:0xf bound_ctrl:1
	s_nop 0
	v_add_f32_dpp v90, v90, v90 row_mirror row_mask:0xf bank_mask:0xf bound_ctrl:1
	v_add_f32_dpp v91, v91, v91 row_mirror row_mask:0xf bank_mask:0xf bound_ctrl:1
	s_waitcnt lgkmcnt(2)
	v_pk_mul_f32 v[0:1], v[0:1], v[16:17] op_sel_hi:[1,0]
	v_pk_mul_f32 v[2:3], v[2:3], v[16:17] op_sel:[0,1]
	v_pk_mul_f32 v[4:5], v[4:5], v[18:19] op_sel_hi:[1,0]
	v_pk_mul_f32 v[6:7], v[6:7], v[18:19] op_sel:[0,1]
	ds_read_b128 v[16:19], v83 offset:2048
	v_pk_fma_f32 v[0:1], v[88:89], v[28:29], v[0:1] op_sel_hi:[1,0,1]
	v_pk_fma_f32 v[2:3], v[88:89], v[28:29], v[2:3] op_sel:[0,1,0]
	v_pk_fma_f32 v[4:5], v[88:89], v[30:31], v[4:5] op_sel_hi:[1,0,1]
	v_pk_fma_f32 v[6:7], v[88:89], v[30:31], v[6:7] op_sel:[0,1,0]
	ds_read_b128 v[28:31], v83 offset:14336
	ds_read_b64 v[88:89], v104 offset:22528
	v_pk_fma_f32 v[0:1], v[90:91], v[24:25], v[0:1] op_sel_hi:[1,0,1] neg_lo:[1,0,0] neg_hi:[1,0,0]
	v_pk_fma_f32 v[2:3], v[90:91], v[24:25], v[2:3] op_sel:[0,1,0] neg_lo:[1,0,0] neg_hi:[1,0,0]
	v_pk_fma_f32 v[4:5], v[90:91], v[26:27], v[4:5] op_sel_hi:[1,0,1] neg_lo:[1,0,0] neg_hi:[1,0,0]
	v_pk_fma_f32 v[6:7], v[90:91], v[26:27], v[6:7] op_sel:[0,1,0] neg_lo:[1,0,0] neg_hi:[1,0,0]
	ds_read_b128 v[24:27], v83 offset:10240
	s_waitcnt lgkmcnt(4)
	v_pk_mul_f32 v[90:91], v[0:1], v[20:21] op_sel_hi:[1,0]
	v_pk_mul_f32 v[92:93], v[0:1], v[84:85] op_sel_hi:[1,0]
	v_pk_fma_f32 v[90:91], v[2:3], v[20:21], v[90:91] op_sel:[0,1,0]
	v_pk_fma_f32 v[92:93], v[2:3], v[84:85], v[92:93] op_sel:[0,1,0]
	v_pk_fma_f32 v[90:91], v[4:5], v[22:23], v[90:91] op_sel_hi:[1,0,1]
	v_pk_fma_f32 v[92:93], v[4:5], v[86:87], v[92:93] op_sel_hi:[1,0,1]
	v_pk_fma_f32 v[90:91], v[6:7], v[22:23], v[90:91] op_sel:[0,1,0]
	v_pk_fma_f32 v[96:97], v[6:7], v[86:87], v[92:93] op_sel:[0,1,0]
	ds_read_b128 v[20:23], v83 offset:6400
	ds_read_b128 v[84:87], v83 offset:18432
	v_add_f32_dpp v90, v90, v90 quad_perm:[1,0,3,2] row_mask:0xf bank_mask:0xf bound_ctrl:1
	v_add_f32_dpp v91, v91, v91 quad_perm:[1,0,3,2] row_mask:0xf bank_mask:0xf bound_ctrl:1
	v_add_f32_dpp v94, v94, v94 row_mirror row_mask:0xf bank_mask:0x3
	v_add_f32_dpp v90, v90, v90 quad_perm:[2,3,0,1] row_mask:0xf bank_mask:0xf bound_ctrl:1
	v_add_f32_dpp v91, v91, v91 quad_perm:[2,3,0,1] row_mask:0xf bank_mask:0xf bound_ctrl:1
	v_add_f32_dpp v95, v95, v95 row_mirror row_mask:0xf bank_mask:0x3
	v_add_f32_dpp v90, v90, v90 row_half_mirror row_mask:0xf bank_mask:0xf bound_ctrl:1
	v_add_f32_dpp v91, v91, v91 row_half_mirror row_mask:0xf bank_mask:0xf bound_ctrl:1
	v_add_f32_dpp v94, v96, v96 row_mirror row_mask:0xf bank_mask:0xc
	v_add_f32_dpp v90, v90, v90 row_mirror row_mask:0xf bank_mask:0xf bound_ctrl:1
	v_add_f32_dpp v91, v91, v91 row_mirror row_mask:0xf bank_mask:0xf bound_ctrl:1
	s_waitcnt lgkmcnt(2)
	v_pk_mul_f32 v[0:1], v[0:1], v[16:17] op_sel_hi:[1,0]
	v_pk_mul_f32 v[2:3], v[2:3], v[16:17] op_sel:[0,1]
	v_pk_mul_f32 v[4:5], v[4:5], v[18:19] op_sel_hi:[1,0]
	v_pk_mul_f32 v[6:7], v[6:7], v[18:19] op_sel:[0,1]
	ds_read_b128 v[16:19], v83 offset:2304
	v_pk_fma_f32 v[0:1], v[88:89], v[28:29], v[0:1] op_sel_hi:[1,0,1]
	v_pk_fma_f32 v[2:3], v[88:89], v[28:29], v[2:3] op_sel:[0,1,0]
	v_pk_fma_f32 v[4:5], v[88:89], v[30:31], v[4:5] op_sel_hi:[1,0,1]
	v_pk_fma_f32 v[6:7], v[88:89], v[30:31], v[6:7] op_sel:[0,1,0]
	ds_read_b128 v[28:31], v83 offset:14592
	ds_read_b64 v[88:89], v104 offset:22784
	v_pk_fma_f32 v[0:1], v[90:91], v[24:25], v[0:1] op_sel_hi:[1,0,1] neg_lo:[1,0,0] neg_hi:[1,0,0]
	v_pk_fma_f32 v[2:3], v[90:91], v[24:25], v[2:3] op_sel:[0,1,0] neg_lo:[1,0,0] neg_hi:[1,0,0]
	v_pk_fma_f32 v[4:5], v[90:91], v[26:27], v[4:5] op_sel_hi:[1,0,1] neg_lo:[1,0,0] neg_hi:[1,0,0]
	v_pk_fma_f32 v[6:7], v[90:91], v[26:27], v[6:7] op_sel:[0,1,0] neg_lo:[1,0,0] neg_hi:[1,0,0]
	ds_read_b128 v[24:27], v83 offset:10496
	v_add_f32_dpp v95, v97, v97 row_mirror row_mask:0xf bank_mask:0xc
	s_waitcnt lgkmcnt(4)
	v_pk_mul_f32 v[90:91], v[0:1], v[20:21] op_sel_hi:[1,0]
	v_pk_mul_f32 v[92:93], v[0:1], v[84:85] op_sel_hi:[1,0]
	v_pk_fma_f32 v[90:91], v[2:3], v[20:21], v[90:91] op_sel:[0,1,0]
	v_pk_fma_f32 v[92:93], v[2:3], v[84:85], v[92:93] op_sel:[0,1,0]
	v_pk_fma_f32 v[90:91], v[4:5], v[22:23], v[90:91] op_sel_hi:[1,0,1]
	v_pk_fma_f32 v[92:93], v[4:5], v[86:87], v[92:93] op_sel_hi:[1,0,1]
	v_pk_fma_f32 v[90:91], v[6:7], v[22:23], v[90:91] op_sel:[0,1,0]
	v_pk_fma_f32 v[98:99], v[6:7], v[86:87], v[92:93] op_sel:[0,1,0]
	ds_read_b128 v[20:23], v83 offset:6656
	ds_read_b128 v[84:87], v83 offset:18688
	v_add_f32_dpp v90, v90, v90 quad_perm:[1,0,3,2] row_mask:0xf bank_mask:0xf bound_ctrl:1
	v_add_f32_dpp v91, v91, v91 quad_perm:[1,0,3,2] row_mask:0xf bank_mask:0xf bound_ctrl:1
	v_add_f32_dpp v70, v70, v70 row_half_mirror row_mask:0xf bank_mask:0x5
	v_add_f32_dpp v90, v90, v90 quad_perm:[2,3,0,1] row_mask:0xf bank_mask:0xf bound_ctrl:1
	v_add_f32_dpp v91, v91, v91 quad_perm:[2,3,0,1] row_mask:0xf bank_mask:0xf bound_ctrl:1
	v_add_f32_dpp v71, v71, v71 row_half_mirror row_mask:0xf bank_mask:0x5
	v_add_f32_dpp v90, v90, v90 row_half_mirror row_mask:0xf bank_mask:0xf bound_ctrl:1
	v_add_f32_dpp v91, v91, v91 row_half_mirror row_mask:0xf bank_mask:0xf bound_ctrl:1
	v_add_f32_dpp v70, v94, v94 row_half_mirror row_mask:0xf bank_mask:0xa
	v_add_f32_dpp v90, v90, v90 row_mirror row_mask:0xf bank_mask:0xf bound_ctrl:1
	v_add_f32_dpp v91, v91, v91 row_mirror row_mask:0xf bank_mask:0xf bound_ctrl:1
	s_waitcnt lgkmcnt(2)
	v_pk_mul_f32 v[0:1], v[0:1], v[16:17] op_sel_hi:[1,0]
	v_pk_mul_f32 v[2:3], v[2:3], v[16:17] op_sel:[0,1]
	v_pk_mul_f32 v[4:5], v[4:5], v[18:19] op_sel_hi:[1,0]
	v_pk_mul_f32 v[6:7], v[6:7], v[18:19] op_sel:[0,1]
	ds_read_b128 v[16:19], v83 offset:2560
	v_pk_fma_f32 v[0:1], v[88:89], v[28:29], v[0:1] op_sel_hi:[1,0,1]
	v_pk_fma_f32 v[2:3], v[88:89], v[28:29], v[2:3] op_sel:[0,1,0]
	v_pk_fma_f32 v[4:5], v[88:89], v[30:31], v[4:5] op_sel_hi:[1,0,1]
	v_pk_fma_f32 v[6:7], v[88:89], v[30:31], v[6:7] op_sel:[0,1,0]
	ds_read_b128 v[28:31], v83 offset:14848
	ds_read_b64 v[88:89], v104 offset:23040
	v_pk_fma_f32 v[0:1], v[90:91], v[24:25], v[0:1] op_sel_hi:[1,0,1] neg_lo:[1,0,0] neg_hi:[1,0,0]
	v_pk_fma_f32 v[2:3], v[90:91], v[24:25], v[2:3] op_sel:[0,1,0] neg_lo:[1,0,0] neg_hi:[1,0,0]
	v_pk_fma_f32 v[4:5], v[90:91], v[26:27], v[4:5] op_sel_hi:[1,0,1] neg_lo:[1,0,0] neg_hi:[1,0,0]
	v_pk_fma_f32 v[6:7], v[90:91], v[26:27], v[6:7] op_sel:[0,1,0] neg_lo:[1,0,0] neg_hi:[1,0,0]
	ds_read_b128 v[24:27], v83 offset:10752
	v_add_f32_dpp v71, v95, v95 row_half_mirror row_mask:0xf bank_mask:0xa
	s_waitcnt lgkmcnt(4)
	v_pk_mul_f32 v[90:91], v[0:1], v[20:21] op_sel_hi:[1,0]
	v_pk_mul_f32 v[92:93], v[0:1], v[84:85] op_sel_hi:[1,0]
	v_pk_fma_f32 v[90:91], v[2:3], v[20:21], v[90:91] op_sel:[0,1,0]
	v_pk_fma_f32 v[92:93], v[2:3], v[84:85], v[92:93] op_sel:[0,1,0]
	v_pk_fma_f32 v[90:91], v[4:5], v[22:23], v[90:91] op_sel_hi:[1,0,1]
	v_pk_fma_f32 v[92:93], v[4:5], v[86:87], v[92:93] op_sel_hi:[1,0,1]
	v_pk_fma_f32 v[90:91], v[6:7], v[22:23], v[90:91] op_sel:[0,1,0]
	v_pk_fma_f32 v[100:101], v[6:7], v[86:87], v[92:93] op_sel:[0,1,0]
	ds_read_b128 v[20:23], v83 offset:6912
	ds_read_b128 v[84:87], v83 offset:18944
	v_add_f32_dpp v90, v90, v90 quad_perm:[1,0,3,2] row_mask:0xf bank_mask:0xf bound_ctrl:1
	v_add_f32_dpp v91, v91, v91 quad_perm:[1,0,3,2] row_mask:0xf bank_mask:0xf bound_ctrl:1
	v_add_f32_dpp v98, v98, v98 row_mirror row_mask:0xf bank_mask:0x3
	v_add_f32_dpp v90, v90, v90 quad_perm:[2,3,0,1] row_mask:0xf bank_mask:0xf bound_ctrl:1
	v_add_f32_dpp v91, v91, v91 quad_perm:[2,3,0,1] row_mask:0xf bank_mask:0xf bound_ctrl:1
	v_add_f32_dpp v99, v99, v99 row_mirror row_mask:0xf bank_mask:0x3
	v_add_f32_dpp v90, v90, v90 row_half_mirror row_mask:0xf bank_mask:0xf bound_ctrl:1
	v_add_f32_dpp v91, v91, v91 row_half_mirror row_mask:0xf bank_mask:0xf bound_ctrl:1
	v_add_f32_dpp v98, v100, v100 row_mirror row_mask:0xf bank_mask:0xc
	v_add_f32_dpp v90, v90, v90 row_mirror row_mask:0xf bank_mask:0xf bound_ctrl:1
	v_add_f32_dpp v91, v91, v91 row_mirror row_mask:0xf bank_mask:0xf bound_ctrl:1
	s_waitcnt lgkmcnt(2)
	v_pk_mul_f32 v[0:1], v[0:1], v[16:17] op_sel_hi:[1,0]
	v_pk_mul_f32 v[2:3], v[2:3], v[16:17] op_sel:[0,1]
	v_pk_mul_f32 v[4:5], v[4:5], v[18:19] op_sel_hi:[1,0]
	v_pk_mul_f32 v[6:7], v[6:7], v[18:19] op_sel:[0,1]
	ds_read_b128 v[16:19], v83 offset:2816
	v_pk_fma_f32 v[0:1], v[88:89], v[28:29], v[0:1] op_sel_hi:[1,0,1]
	v_pk_fma_f32 v[2:3], v[88:89], v[28:29], v[2:3] op_sel:[0,1,0]
	v_pk_fma_f32 v[4:5], v[88:89], v[30:31], v[4:5] op_sel_hi:[1,0,1]
	v_pk_fma_f32 v[6:7], v[88:89], v[30:31], v[6:7] op_sel:[0,1,0]
	ds_read_b128 v[28:31], v83 offset:15104
	ds_read_b64 v[88:89], v104 offset:23296
	v_pk_fma_f32 v[0:1], v[90:91], v[24:25], v[0:1] op_sel_hi:[1,0,1] neg_lo:[1,0,0] neg_hi:[1,0,0]
	v_pk_fma_f32 v[2:3], v[90:91], v[24:25], v[2:3] op_sel:[0,1,0] neg_lo:[1,0,0] neg_hi:[1,0,0]
	v_pk_fma_f32 v[4:5], v[90:91], v[26:27], v[4:5] op_sel_hi:[1,0,1] neg_lo:[1,0,0] neg_hi:[1,0,0]
	v_pk_fma_f32 v[6:7], v[90:91], v[26:27], v[6:7] op_sel:[0,1,0] neg_lo:[1,0,0] neg_hi:[1,0,0]
	ds_read_b128 v[24:27], v83 offset:11008
	v_add_f32_dpp v99, v101, v101 row_mirror row_mask:0xf bank_mask:0xc
	s_waitcnt lgkmcnt(4)
	v_pk_mul_f32 v[90:91], v[0:1], v[20:21] op_sel_hi:[1,0]
	v_pk_mul_f32 v[92:93], v[0:1], v[84:85] op_sel_hi:[1,0]
	v_pk_fma_f32 v[90:91], v[2:3], v[20:21], v[90:91] op_sel:[0,1,0]
	v_pk_fma_f32 v[92:93], v[2:3], v[84:85], v[92:93] op_sel:[0,1,0]
	v_pk_fma_f32 v[90:91], v[4:5], v[22:23], v[90:91] op_sel_hi:[1,0,1]
	v_pk_fma_f32 v[92:93], v[4:5], v[86:87], v[92:93] op_sel_hi:[1,0,1]
	v_pk_fma_f32 v[90:91], v[6:7], v[22:23], v[90:91] op_sel:[0,1,0]
	v_pk_fma_f32 v[102:103], v[6:7], v[86:87], v[92:93] op_sel:[0,1,0]
	ds_read_b128 v[20:23], v83 offset:7168
	ds_read_b128 v[84:87], v83 offset:19200
	v_add_f32_dpp v90, v90, v90 quad_perm:[1,0,3,2] row_mask:0xf bank_mask:0xf bound_ctrl:1
	v_add_f32_dpp v91, v91, v91 quad_perm:[1,0,3,2] row_mask:0xf bank_mask:0xf bound_ctrl:1
	v_add_f32_dpp v8, v8, v8 quad_perm:[2,3,0,1] row_mask:0xf bank_mask:0xf bound_ctrl:1
	v_add_f32_dpp v90, v90, v90 quad_perm:[2,3,0,1] row_mask:0xf bank_mask:0xf bound_ctrl:1
	v_add_f32_dpp v91, v91, v91 quad_perm:[2,3,0,1] row_mask:0xf bank_mask:0xf bound_ctrl:1
	v_add_f32_dpp v70, v70, v70 quad_perm:[2,3,0,1] row_mask:0xf bank_mask:0xf bound_ctrl:1
	v_add_f32_dpp v90, v90, v90 row_half_mirror row_mask:0xf bank_mask:0xf bound_ctrl:1
	v_add_f32_dpp v91, v91, v91 row_half_mirror row_mask:0xf bank_mask:0xf bound_ctrl:1
	v_add_f32_dpp v9, v9, v9 quad_perm:[2,3,0,1] row_mask:0xf bank_mask:0xf bound_ctrl:1
	v_add_f32_dpp v90, v90, v90 row_mirror row_mask:0xf bank_mask:0xf bound_ctrl:1
	v_add_f32_dpp v91, v91, v91 row_mirror row_mask:0xf bank_mask:0xf bound_ctrl:1
	s_waitcnt lgkmcnt(2)
	v_pk_mul_f32 v[0:1], v[0:1], v[16:17] op_sel_hi:[1,0]
	v_pk_mul_f32 v[2:3], v[2:3], v[16:17] op_sel:[0,1]
	v_pk_mul_f32 v[4:5], v[4:5], v[18:19] op_sel_hi:[1,0]
	v_pk_mul_f32 v[6:7], v[6:7], v[18:19] op_sel:[0,1]
	ds_read_b128 v[16:19], v83 offset:3072
	v_pk_fma_f32 v[0:1], v[88:89], v[28:29], v[0:1] op_sel_hi:[1,0,1]
	v_pk_fma_f32 v[2:3], v[88:89], v[28:29], v[2:3] op_sel:[0,1,0]
	v_pk_fma_f32 v[4:5], v[88:89], v[30:31], v[4:5] op_sel_hi:[1,0,1]
	v_pk_fma_f32 v[6:7], v[88:89], v[30:31], v[6:7] op_sel:[0,1,0]
	ds_read_b128 v[28:31], v83 offset:15360
	ds_read_b64 v[88:89], v104 offset:23552
	v_pk_fma_f32 v[0:1], v[90:91], v[24:25], v[0:1] op_sel_hi:[1,0,1] neg_lo:[1,0,0] neg_hi:[1,0,0]
	v_pk_fma_f32 v[2:3], v[90:91], v[24:25], v[2:3] op_sel:[0,1,0] neg_lo:[1,0,0] neg_hi:[1,0,0]
	v_pk_fma_f32 v[4:5], v[90:91], v[26:27], v[4:5] op_sel_hi:[1,0,1] neg_lo:[1,0,0] neg_hi:[1,0,0]
	v_pk_fma_f32 v[6:7], v[90:91], v[26:27], v[6:7] op_sel:[0,1,0] neg_lo:[1,0,0] neg_hi:[1,0,0]
	ds_read_b128 v[24:27], v83 offset:11264
	v_add_f32_dpp v71, v71, v71 quad_perm:[2,3,0,1] row_mask:0xf bank_mask:0xf bound_ctrl:1
	s_waitcnt lgkmcnt(4)
	v_pk_mul_f32 v[90:91], v[0:1], v[20:21] op_sel_hi:[1,0]
	v_pk_mul_f32 v[92:93], v[0:1], v[84:85] op_sel_hi:[1,0]
	v_pk_fma_f32 v[90:91], v[2:3], v[20:21], v[90:91] op_sel:[0,1,0]
	v_pk_fma_f32 v[92:93], v[2:3], v[84:85], v[92:93] op_sel:[0,1,0]
	v_pk_fma_f32 v[90:91], v[4:5], v[22:23], v[90:91] op_sel_hi:[1,0,1]
	v_pk_fma_f32 v[92:93], v[4:5], v[86:87], v[92:93] op_sel_hi:[1,0,1]
	v_pk_fma_f32 v[90:91], v[6:7], v[22:23], v[90:91] op_sel:[0,1,0]
	v_pk_fma_f32 v[10:11], v[6:7], v[86:87], v[92:93] op_sel:[0,1,0]
	ds_read_b128 v[20:23], v83 offset:7424
	ds_read_b128 v[84:87], v83 offset:19456
	v_add_f32_dpp v90, v90, v90 quad_perm:[1,0,3,2] row_mask:0xf bank_mask:0xf bound_ctrl:1
	v_add_f32_dpp v91, v91, v91 quad_perm:[1,0,3,2] row_mask:0xf bank_mask:0xf bound_ctrl:1
	v_add_f32_dpp v102, v102, v102 row_mirror row_mask:0xf bank_mask:0x3
	v_add_f32_dpp v90, v90, v90 quad_perm:[2,3,0,1] row_mask:0xf bank_mask:0xf bound_ctrl:1
	v_add_f32_dpp v91, v91, v91 quad_perm:[2,3,0,1] row_mask:0xf bank_mask:0xf bound_ctrl:1
	v_add_f32_dpp v103, v103, v103 row_mirror row_mask:0xf bank_mask:0x3
	v_add_f32_dpp v90, v90, v90 row_half_mirror row_mask:0xf bank_mask:0xf bound_ctrl:1
	v_add_f32_dpp v91, v91, v91 row_half_mirror row_mask:0xf bank_mask:0xf bound_ctrl:1
	v_add_f32_dpp v102, v10, v10 row_mirror row_mask:0xf bank_mask:0xc
	v_add_f32_dpp v90, v90, v90 row_mirror row_mask:0xf bank_mask:0xf bound_ctrl:1
	v_add_f32_dpp v91, v91, v91 row_mirror row_mask:0xf bank_mask:0xf bound_ctrl:1
	s_waitcnt lgkmcnt(2)
	v_pk_mul_f32 v[0:1], v[0:1], v[16:17] op_sel_hi:[1,0]
	v_pk_mul_f32 v[2:3], v[2:3], v[16:17] op_sel:[0,1]
	v_pk_mul_f32 v[4:5], v[4:5], v[18:19] op_sel_hi:[1,0]
	v_pk_mul_f32 v[6:7], v[6:7], v[18:19] op_sel:[0,1]
	ds_read_b128 v[16:19], v83 offset:3328
	v_pk_fma_f32 v[0:1], v[88:89], v[28:29], v[0:1] op_sel_hi:[1,0,1]
	v_pk_fma_f32 v[2:3], v[88:89], v[28:29], v[2:3] op_sel:[0,1,0]
	v_pk_fma_f32 v[4:5], v[88:89], v[30:31], v[4:5] op_sel_hi:[1,0,1]
	v_pk_fma_f32 v[6:7], v[88:89], v[30:31], v[6:7] op_sel:[0,1,0]
	ds_read_b128 v[28:31], v83 offset:15616
	ds_read_b64 v[88:89], v104 offset:23808
	v_pk_fma_f32 v[0:1], v[90:91], v[24:25], v[0:1] op_sel_hi:[1,0,1] neg_lo:[1,0,0] neg_hi:[1,0,0]
	v_pk_fma_f32 v[2:3], v[90:91], v[24:25], v[2:3] op_sel:[0,1,0] neg_lo:[1,0,0] neg_hi:[1,0,0]
	v_pk_fma_f32 v[4:5], v[90:91], v[26:27], v[4:5] op_sel_hi:[1,0,1] neg_lo:[1,0,0] neg_hi:[1,0,0]
	v_pk_fma_f32 v[6:7], v[90:91], v[26:27], v[6:7] op_sel:[0,1,0] neg_lo:[1,0,0] neg_hi:[1,0,0]
	ds_read_b128 v[24:27], v83 offset:11520
	v_add_f32_dpp v103, v11, v11 row_mirror row_mask:0xf bank_mask:0xc
	s_waitcnt lgkmcnt(4)
	v_pk_mul_f32 v[90:91], v[0:1], v[20:21] op_sel_hi:[1,0]
	v_pk_mul_f32 v[92:93], v[0:1], v[84:85] op_sel_hi:[1,0]
	v_pk_fma_f32 v[90:91], v[2:3], v[20:21], v[90:91] op_sel:[0,1,0]
	v_pk_fma_f32 v[92:93], v[2:3], v[84:85], v[92:93] op_sel:[0,1,0]
	v_pk_fma_f32 v[90:91], v[4:5], v[22:23], v[90:91] op_sel_hi:[1,0,1]
	v_pk_fma_f32 v[92:93], v[4:5], v[86:87], v[92:93] op_sel_hi:[1,0,1]
	v_pk_fma_f32 v[90:91], v[6:7], v[22:23], v[90:91] op_sel:[0,1,0]
	v_pk_fma_f32 v[14:15], v[6:7], v[86:87], v[92:93] op_sel:[0,1,0]
	ds_read_b128 v[20:23], v83 offset:7680
	ds_read_b128 v[84:87], v83 offset:19712
	v_add_f32_dpp v90, v90, v90 quad_perm:[1,0,3,2] row_mask:0xf bank_mask:0xf bound_ctrl:1
	v_add_f32_dpp v91, v91, v91 quad_perm:[1,0,3,2] row_mask:0xf bank_mask:0xf bound_ctrl:1
	v_add_f32_dpp v98, v98, v98 row_half_mirror row_mask:0xf bank_mask:0x5
	v_add_f32_dpp v90, v90, v90 quad_perm:[2,3,0,1] row_mask:0xf bank_mask:0xf bound_ctrl:1
	v_add_f32_dpp v91, v91, v91 quad_perm:[2,3,0,1] row_mask:0xf bank_mask:0xf bound_ctrl:1
	v_add_f32_dpp v99, v99, v99 row_half_mirror row_mask:0xf bank_mask:0x5
	v_add_f32_dpp v90, v90, v90 row_half_mirror row_mask:0xf bank_mask:0xf bound_ctrl:1
	v_add_f32_dpp v91, v91, v91 row_half_mirror row_mask:0xf bank_mask:0xf bound_ctrl:1
	v_add_f32_dpp v98, v102, v102 row_half_mirror row_mask:0xf bank_mask:0xa
	v_add_f32_dpp v90, v90, v90 row_mirror row_mask:0xf bank_mask:0xf bound_ctrl:1
	v_add_f32_dpp v91, v91, v91 row_mirror row_mask:0xf bank_mask:0xf bound_ctrl:1
	s_waitcnt lgkmcnt(2)
	v_pk_mul_f32 v[0:1], v[0:1], v[16:17] op_sel_hi:[1,0]
	v_pk_mul_f32 v[2:3], v[2:3], v[16:17] op_sel:[0,1]
	v_pk_mul_f32 v[4:5], v[4:5], v[18:19] op_sel_hi:[1,0]
	v_pk_mul_f32 v[6:7], v[6:7], v[18:19] op_sel:[0,1]
	ds_read_b128 v[16:19], v83 offset:3584
	v_pk_fma_f32 v[0:1], v[88:89], v[28:29], v[0:1] op_sel_hi:[1,0,1]
	v_pk_fma_f32 v[2:3], v[88:89], v[28:29], v[2:3] op_sel:[0,1,0]
	v_pk_fma_f32 v[4:5], v[88:89], v[30:31], v[4:5] op_sel_hi:[1,0,1]
	v_pk_fma_f32 v[6:7], v[88:89], v[30:31], v[6:7] op_sel:[0,1,0]
	ds_read_b128 v[28:31], v83 offset:15872
	ds_read_b64 v[88:89], v104 offset:24064
	v_pk_fma_f32 v[0:1], v[90:91], v[24:25], v[0:1] op_sel_hi:[1,0,1] neg_lo:[1,0,0] neg_hi:[1,0,0]
	v_pk_fma_f32 v[2:3], v[90:91], v[24:25], v[2:3] op_sel:[0,1,0] neg_lo:[1,0,0] neg_hi:[1,0,0]
	v_pk_fma_f32 v[4:5], v[90:91], v[26:27], v[4:5] op_sel_hi:[1,0,1] neg_lo:[1,0,0] neg_hi:[1,0,0]
	v_pk_fma_f32 v[6:7], v[90:91], v[26:27], v[6:7] op_sel:[0,1,0] neg_lo:[1,0,0] neg_hi:[1,0,0]
	ds_read_b128 v[24:27], v83 offset:11776
	v_add_f32_dpp v99, v103, v103 row_half_mirror row_mask:0xf bank_mask:0xa
	s_waitcnt lgkmcnt(4)
	v_pk_mul_f32 v[90:91], v[0:1], v[20:21] op_sel_hi:[1,0]
	v_pk_mul_f32 v[92:93], v[0:1], v[84:85] op_sel_hi:[1,0]
	v_pk_fma_f32 v[90:91], v[2:3], v[20:21], v[90:91] op_sel:[0,1,0]
	v_pk_fma_f32 v[92:93], v[2:3], v[84:85], v[92:93] op_sel:[0,1,0]
	v_pk_fma_f32 v[90:91], v[4:5], v[22:23], v[90:91] op_sel_hi:[1,0,1]
	v_pk_fma_f32 v[92:93], v[4:5], v[86:87], v[92:93] op_sel_hi:[1,0,1]
	v_pk_fma_f32 v[90:91], v[6:7], v[22:23], v[90:91] op_sel:[0,1,0]
	v_pk_fma_f32 v[12:13], v[6:7], v[86:87], v[92:93] op_sel:[0,1,0]
	ds_read_b128 v[20:23], v83 offset:7936
	ds_read_b128 v[84:87], v83 offset:19968
	v_add_f32_dpp v90, v90, v90 quad_perm:[1,0,3,2] row_mask:0xf bank_mask:0xf bound_ctrl:1
	v_add_f32_dpp v91, v91, v91 quad_perm:[1,0,3,2] row_mask:0xf bank_mask:0xf bound_ctrl:1
	v_add_f32_dpp v14, v14, v14 row_mirror row_mask:0xf bank_mask:0x3
	v_add_f32_dpp v90, v90, v90 quad_perm:[2,3,0,1] row_mask:0xf bank_mask:0xf bound_ctrl:1
	v_add_f32_dpp v91, v91, v91 quad_perm:[2,3,0,1] row_mask:0xf bank_mask:0xf bound_ctrl:1
	v_add_f32_dpp v15, v15, v15 row_mirror row_mask:0xf bank_mask:0x3
	v_add_f32_dpp v90, v90, v90 row_half_mirror row_mask:0xf bank_mask:0xf bound_ctrl:1
	v_add_f32_dpp v91, v91, v91 row_half_mirror row_mask:0xf bank_mask:0xf bound_ctrl:1
	v_add_f32_dpp v14, v12, v12 row_mirror row_mask:0xf bank_mask:0xc
	v_add_f32_dpp v90, v90, v90 row_mirror row_mask:0xf bank_mask:0xf bound_ctrl:1
	v_add_f32_dpp v91, v91, v91 row_mirror row_mask:0xf bank_mask:0xf bound_ctrl:1
	s_waitcnt lgkmcnt(2)
	v_pk_mul_f32 v[0:1], v[0:1], v[16:17] op_sel_hi:[1,0]
	v_pk_mul_f32 v[2:3], v[2:3], v[16:17] op_sel:[0,1]
	v_pk_mul_f32 v[4:5], v[4:5], v[18:19] op_sel_hi:[1,0]
	v_pk_mul_f32 v[6:7], v[6:7], v[18:19] op_sel:[0,1]
	ds_read_b128 v[16:19], v83 offset:3840
	v_pk_fma_f32 v[0:1], v[88:89], v[28:29], v[0:1] op_sel_hi:[1,0,1]
	v_pk_fma_f32 v[2:3], v[88:89], v[28:29], v[2:3] op_sel:[0,1,0]
	v_pk_fma_f32 v[4:5], v[88:89], v[30:31], v[4:5] op_sel_hi:[1,0,1]
	v_pk_fma_f32 v[6:7], v[88:89], v[30:31], v[6:7] op_sel:[0,1,0]
	ds_read_b128 v[28:31], v83 offset:16128
	ds_read_b64 v[88:89], v104 offset:24320
	v_pk_fma_f32 v[0:1], v[90:91], v[24:25], v[0:1] op_sel_hi:[1,0,1] neg_lo:[1,0,0] neg_hi:[1,0,0]
	v_pk_fma_f32 v[2:3], v[90:91], v[24:25], v[2:3] op_sel:[0,1,0] neg_lo:[1,0,0] neg_hi:[1,0,0]
	v_pk_fma_f32 v[4:5], v[90:91], v[26:27], v[4:5] op_sel_hi:[1,0,1] neg_lo:[1,0,0] neg_hi:[1,0,0]
	v_pk_fma_f32 v[6:7], v[90:91], v[26:27], v[6:7] op_sel:[0,1,0] neg_lo:[1,0,0] neg_hi:[1,0,0]
	ds_read_b128 v[24:27], v83 offset:12032
	v_add_f32_dpp v15, v13, v13 row_mirror row_mask:0xf bank_mask:0xc
	s_waitcnt lgkmcnt(4)
	v_pk_mul_f32 v[90:91], v[0:1], v[20:21] op_sel_hi:[1,0]
	v_pk_mul_f32 v[92:93], v[0:1], v[84:85] op_sel_hi:[1,0]
	v_pk_fma_f32 v[90:91], v[2:3], v[20:21], v[90:91] op_sel:[0,1,0]
	v_pk_fma_f32 v[92:93], v[2:3], v[84:85], v[92:93] op_sel:[0,1,0]
	v_pk_fma_f32 v[90:91], v[4:5], v[22:23], v[90:91] op_sel_hi:[1,0,1]
	v_pk_fma_f32 v[92:93], v[4:5], v[86:87], v[92:93] op_sel_hi:[1,0,1]
	v_pk_fma_f32 v[90:91], v[6:7], v[22:23], v[90:91] op_sel:[0,1,0]
	v_pk_fma_f32 v[72:73], v[6:7], v[86:87], v[92:93] op_sel:[0,1,0]
	ds_read_b128 v[84:87], v83 offset:20224
	v_add_f32_dpp v90, v90, v90 quad_perm:[1,0,3,2] row_mask:0xf bank_mask:0xf bound_ctrl:1
	v_add_f32_dpp v91, v91, v91 quad_perm:[1,0,3,2] row_mask:0xf bank_mask:0xf bound_ctrl:1
	v_cndmask_b32_e64 v8, v8, v70, s[46:47]
	v_add_f32_dpp v90, v90, v90 quad_perm:[2,3,0,1] row_mask:0xf bank_mask:0xf bound_ctrl:1
	v_add_f32_dpp v91, v91, v91 quad_perm:[2,3,0,1] row_mask:0xf bank_mask:0xf bound_ctrl:1
	v_cndmask_b32_e64 v9, v9, v71, s[46:47]
	v_add_f32_dpp v90, v90, v90 row_half_mirror row_mask:0xf bank_mask:0xf bound_ctrl:1
	v_add_f32_dpp v91, v91, v91 row_half_mirror row_mask:0xf bank_mask:0xf bound_ctrl:1
	s_nop 0
	v_add_f32_dpp v90, v90, v90 row_mirror row_mask:0xf bank_mask:0xf bound_ctrl:1
	v_add_f32_dpp v91, v91, v91 row_mirror row_mask:0xf bank_mask:0xf bound_ctrl:1
	s_waitcnt lgkmcnt(1)
	v_pk_mul_f32 v[0:1], v[0:1], v[16:17] op_sel_hi:[1,0]
	v_pk_mul_f32 v[2:3], v[2:3], v[16:17] op_sel:[0,1]
	v_pk_mul_f32 v[4:5], v[4:5], v[18:19] op_sel_hi:[1,0]
	v_pk_mul_f32 v[6:7], v[6:7], v[18:19] op_sel:[0,1]
	v_pk_fma_f32 v[0:1], v[88:89], v[28:29], v[0:1] op_sel_hi:[1,0,1]
	v_pk_fma_f32 v[2:3], v[88:89], v[28:29], v[2:3] op_sel:[0,1,0]
	v_pk_fma_f32 v[4:5], v[88:89], v[30:31], v[4:5] op_sel_hi:[1,0,1]
	v_pk_fma_f32 v[6:7], v[88:89], v[30:31], v[6:7] op_sel:[0,1,0]
	v_pk_fma_f32 v[0:1], v[90:91], v[24:25], v[0:1] op_sel_hi:[1,0,1] neg_lo:[1,0,0] neg_hi:[1,0,0]
	v_pk_fma_f32 v[2:3], v[90:91], v[24:25], v[2:3] op_sel:[0,1,0] neg_lo:[1,0,0] neg_hi:[1,0,0]
	v_pk_fma_f32 v[4:5], v[90:91], v[26:27], v[4:5] op_sel_hi:[1,0,1] neg_lo:[1,0,0] neg_hi:[1,0,0]
	v_pk_fma_f32 v[6:7], v[90:91], v[26:27], v[6:7] op_sel:[0,1,0] neg_lo:[1,0,0] neg_hi:[1,0,0]
	s_waitcnt lgkmcnt(0)
	v_pk_mul_f32 v[92:93], v[0:1], v[84:85] op_sel_hi:[1,0]
	v_pk_fma_f32 v[92:93], v[2:3], v[84:85], v[92:93] op_sel:[0,1,0]
	v_pk_fma_f32 v[92:93], v[4:5], v[86:87], v[92:93] op_sel_hi:[1,0,1]
	v_pk_fma_f32 v[96:97], v[6:7], v[86:87], v[92:93] op_sel:[0,1,0]
	v_bfrev_b32_e32 v105, v33
	v_lshrrev_b32_e32 v105, 28, v105
	v_add_f32_dpp v72, v72, v72 row_mirror row_mask:0xf bank_mask:0x3
	v_add_f32_dpp v73, v73, v73 row_mirror row_mask:0xf bank_mask:0x3
	v_add_f32_dpp v72, v96, v96 row_mirror row_mask:0xf bank_mask:0xc
	v_add_f32_dpp v73, v97, v97 row_mirror row_mask:0xf bank_mask:0xc
	v_add_f32_dpp v14, v14, v14 row_half_mirror row_mask:0xf bank_mask:0x5
	v_add_f32_dpp v15, v15, v15 row_half_mirror row_mask:0xf bank_mask:0x5
	v_add_f32_dpp v14, v72, v72 row_half_mirror row_mask:0xf bank_mask:0xa
	v_add_f32_dpp v15, v73, v73 row_half_mirror row_mask:0xf bank_mask:0xa
	v_add_f32_dpp v98, v98, v98 quad_perm:[2,3,0,1] row_mask:0xf bank_mask:0xf bound_ctrl:1
	v_add_f32_dpp v14, v14, v14 quad_perm:[2,3,0,1] row_mask:0xf bank_mask:0xf bound_ctrl:1
	v_add_f32_dpp v99, v99, v99 quad_perm:[2,3,0,1] row_mask:0xf bank_mask:0xf bound_ctrl:1
	v_add_f32_dpp v15, v15, v15 quad_perm:[2,3,0,1] row_mask:0xf bank_mask:0xf bound_ctrl:1
	v_cndmask_b32_e64 v98, v98, v14, s[46:47]
	v_cndmask_b32_e64 v99, v99, v15, s[46:47]
	v_add_u32_e32 v105, s83, v105
	v_add_u32_e32 v105, s26, v105
	v_add_f32_dpp v8, v8, v8 quad_perm:[1,0,3,2] row_mask:0xf bank_mask:0xf bound_ctrl:1
	v_add_f32_dpp v98, v98, v98 quad_perm:[1,0,3,2] row_mask:0xf bank_mask:0xf bound_ctrl:1
	v_add_f32_dpp v9, v9, v9 quad_perm:[1,0,3,2] row_mask:0xf bank_mask:0xf bound_ctrl:1
	v_add_f32_dpp v99, v99, v99 quad_perm:[1,0,3,2] row_mask:0xf bank_mask:0xf bound_ctrl:1
	v_cndmask_b32_e64 v8, v8, v98, s[44:45]
	v_cndmask_b32_e64 v9, v9, v99, s[44:45]
	v_lshlrev_b32_e32 v104, 12, v105
	v_mov_b32_e32 v105, 0
	v_lshl_add_u64 v[104:105], v[64:65], 0, v[104:105]
	global_store_dwordx2 v[104:105], v[8:9], off
	s_setprio 0
	s_branch .LBB0_4107
